# scan_dn MFMA stage with 4-slot LDS fragment ring + pass-C item rebalance (on top of copies/nscan)
# baseline (speedup 1.0000x reference)
.LBB0_635:
	s_or_b64 exec, exec, s[4:5]
	v_readlane_b32 s4, v238, 33
	v_readlane_b32 s5, v238, 34
	v_readlane_b32 s50, v238, 17
	s_andn2_b64 vcc, exec, s[4:5]
	v_readlane_b32 s51, v238, 18
	v_readlane_b32 s96, v238, 29
	s_barrier
	s_cbranch_vccnz .LBB0_662
	v_readlane_b32 s101, v239, 2
	s_mov_b32 s100, 0x200
	s_cmp_lg_u32 s101, 0x100
	s_cbranch_scc1 .Lrebal_done
	s_cmp_lt_i32 s68, 64
	s_cbranch_scc1 .Lrebal_a
	s_cmpk_lt_i32 s68, 0xc0
	s_cbranch_scc1 .Lrebal_b
	s_add_i32 s68, s68, 0xc0
	s_mov_b32 s16, 32
	s_mov_b32 s100, 0x1c0
	s_branch .Lrebal_done
.Lrebal_a:
	s_add_i32 s68, s68, 0x1c0
	s_branch .Lrebal_done
.Lrebal_b:
	s_add_i32 s68, s68, 0xffffffc0
	s_movk_i32 s16, 0x80
	s_mov_b32 s100, 0x180
.Lrebal_done:
	s_lshl_b32 s14, s68, 4
	v_readlane_b32 s4, v239, 2
	s_mov_b32 s6, s4
	v_readlane_b32 s5, v239, 3
	s_lshl_b32 s15, s16, 4
	s_lshl_b32 s18, s68, 6
	s_lshl_b32 s19, s16, 6
	s_ashr_i32 s69, s68, 31
	s_lshl_b64 s[4:5], s[68:69], 4
	s_add_u32 s33, s4, 0x17fe9004
	s_addc_u32 s35, s5, 0
	s_ashr_i32 s17, s16, 31
	s_lshl_b64 s[22:23], s[16:17], 4
	s_lshl_b64 s[24:25], s[68:69], 9
	s_lshl_b64 s[26:27], s[16:17], 9
	s_lshl_b64 s[4:5], s[68:69], 16
	s_add_u32 s4, s28, s4
	s_addc_u32 s5, s29, s5
	v_mbcnt_lo_u32_b32 v0, -1, 0
	s_add_u32 s36, s4, 0x2000000
	v_mbcnt_hi_u32_b32 v83, -1, v0
	s_addc_u32 s37, s5, 0
	s_lshl_b64 s[38:39], s[16:17], 16
	s_mov_b32 s41, 0
	v_mov_b32_e32 v77, 0x3ecc95a3
	v_mov_b32_e32 v80, 0x7f800000
	v_mov_b32_e32 v81, 0x7fc00000
	v_mov_b32_e32 v82, 0xff800000
	v_and_b32_e32 v84, 64, v83
	v_add_u32_e32 v85, -1, v83
	v_add_u32_e32 v86, -2, v83
	v_add_u32_e32 v87, -4, v83
	v_add_u32_e32 v88, -8, v83
	v_add_u32_e32 v89, -16, v83
	v_subrev_u32_e32 v90, 32, v83
	v_mov_b32_e32 v73, 0
	s_movk_i32 s17, 0x2000
	s_movk_i32 s42, 0x110
	s_add_i32 s43, 0, 0x11800
	s_movk_i32 s44, 0x90
	v_mov_b32_e32 v91, 0x358637bd
	s_mov_b32 s45, s68
	s_branch .LBB0_638
.LBB0_637:
	s_or_b64 exec, exec, s[4:5]
	v_lshl_or_b32 v64, v95, 5, v93
	v_mad_u64_u32 v[68:69], s[4:5], v64, s44, v[76:77]
	v_mul_u32_u24_e32 v76, 0x90, v93
	v_add3_u32 v76, s43, v96, v76
	ds_read_b128 v[98:101], v68 offset:34816
	ds_read_b128 v[102:105], v68 offset:37120
	s_waitcnt lgkmcnt(2)
	ds_read_b128 v[64:67], v68 offset:34880
	ds_read_b128 v[68:71], v68 offset:37184
	ds_read_b128 v[106:109], v76
	v_pk_mul_f32 v[50:51], v[50:51], v[62:63]
	v_pk_mul_f32 v[48:49], v[48:49], v[60:61]
	v_pk_mul_f32 v[46:47], v[46:47], v[62:63]
	v_pk_mul_f32 v[44:45], v[44:45], v[60:61]
	ds_read_b128 v[60:63], v76 offset:64
	s_waitcnt lgkmcnt(1)
	v_mfma_f32_16x16x32_bf16 v[48:51], v[106:109], v[98:101], v[48:51]
	v_mul_f32_e64 v38, v38, v58
	v_mul_f32_e64 v39, v39, v59
	v_pk_mul_f32 v[36:37], v[36:37], v[56:57]
	v_pk_mul_f32 v[34:35], v[34:35], v[58:59]
	v_mfma_f32_16x16x32_bf16 v[44:47], v[106:109], v[102:105], v[44:47]
	v_mul_f32_e64 v32, v32, v56
	v_mul_f32_e64 v33, v33, v57
	ds_read_b128 v[56:59], v76 offset:2368
	v_pk_mul_f32 v[30:31], v[30:31], v[54:55]
	s_waitcnt lgkmcnt(1)
	v_mfma_f32_16x16x32_bf16 v[48:51], v[60:63], v[64:67], v[48:51]
	v_mul_f32_e64 v28, v28, v52
	v_mul_f32_e64 v29, v29, v53
	v_pk_mul_f32 v[26:27], v[26:27], v[54:55]
	v_pk_mul_f32 v[24:25], v[24:25], v[52:53]
	v_mfma_f32_16x16x32_bf16 v[44:47], v[60:63], v[68:71], v[44:47]
	ds_read_b128 v[60:63], v76 offset:2304
	ds_read_b128 v[52:55], v76 offset:4672
	v_pk_mul_f32 v[22:23], v[22:23], v[42:43]
	s_waitcnt lgkmcnt(1)
	v_mfma_f32_16x16x32_bf16 v[36:39], v[60:63], v[98:101], v[36:39]
	v_mul_f32_e64 v20, v20, v40
	v_mul_f32_e64 v21, v21, v41
	v_pk_mul_f32 v[18:19], v[18:19], v[42:43]
	v_pk_mul_f32 v[16:17], v[16:17], v[40:41]
	v_mfma_f32_16x16x32_bf16 v[32:35], v[60:63], v[102:105], v[32:35]
	ds_read_b128 v[40:43], v76 offset:6976
	s_movk_i32 s4, 0x410
	v_ashrrev_i32_e32 v75, 31, v74
	v_mfma_f32_16x16x32_bf16 v[36:39], v[56:59], v[64:67], v[36:39]
	v_lshlrev_b32_e32 v60, 16, v13
	v_and_b32_e32 v61, 0xffff0000, v13
	v_lshlrev_b32_e32 v62, 16, v14
	v_mfma_f32_16x16x32_bf16 v[32:35], v[56:59], v[68:71], v[32:35]
	ds_read_b128 v[56:59], v76 offset:4608
	v_and_b32_e32 v63, 0xffff0000, v14
	s_mov_b64 s[6:7], 0x10e00800
	s_waitcnt lgkmcnt(0)
	v_mfma_f32_16x16x32_bf16 v[28:31], v[56:59], v[98:101], v[28:31]
	v_mfma_f32_16x16x32_bf16 v[24:27], v[56:59], v[102:105], v[24:27]
	v_mfma_f32_16x16x32_bf16 v[28:31], v[52:55], v[64:67], v[28:31]
	v_mfma_f32_16x16x32_bf16 v[24:27], v[52:55], v[68:71], v[24:27]
	ds_read_b128 v[52:55], v76 offset:6912
	s_waitcnt lgkmcnt(0)
	s_barrier
	v_mfma_f32_16x16x32_bf16 v[20:23], v[52:55], v[98:101], v[20:23]
	v_mfma_f32_16x16x32_bf16 v[16:19], v[52:55], v[102:105], v[16:19]
	v_lshlrev_b32_e32 v52, 2, v93
	v_lshlrev_b32_e32 v53, 2, v72
	v_lshlrev_b32_e32 v72, 1, v72
	v_mfma_f32_16x16x32_bf16 v[20:23], v[40:43], v[64:67], v[20:23]
	v_lshlrev_b32_e32 v64, 16, v15
	v_and_b32_e32 v65, 0xffff0000, v15
	v_mfma_f32_16x16x32_bf16 v[16:19], v[40:43], v[68:71], v[16:19]
	v_lshl_add_u32 v41, v94, 2, 0
	v_add_u32_e32 v41, 0x14000, v41
	ds_read_b32 v42, v41
	v_lshl_add_u32 v40, v95, 7, 0
	s_waitcnt lgkmcnt(0)
	v_mul_f32_e32 v43, v48, v42
	v_mul_u32_u24_e32 v48, 0x410, v94
	v_add3_u32 v40, v40, v48, v52
	v_mul_f32_e32 v42, v44, v42
	ds_write2_b32 v40, v43, v42 offset1:16
	ds_read_b32 v42, v41 offset:4
	v_add_u32_e32 v44, 0x400, v40
	s_waitcnt lgkmcnt(0)
	v_mul_f32_e32 v43, v49, v42
	v_mul_f32_e32 v42, v45, v42
	ds_write2_b32 v44, v43, v42 offset0:4 offset1:20
	ds_read_b32 v42, v41 offset:8
	v_add_u32_e32 v44, 0x800, v40
	s_waitcnt lgkmcnt(0)
	v_mul_f32_e32 v43, v50, v42
	v_mul_f32_e32 v42, v46, v42
	ds_write2_b32 v44, v43, v42 offset0:8 offset1:24
	ds_read_b32 v42, v41 offset:12
	v_add_u32_e32 v44, 0xc00, v40
	s_waitcnt lgkmcnt(0)
	v_mul_f32_e32 v43, v51, v42
	v_mul_f32_e32 v42, v47, v42
	ds_write2_b32 v44, v43, v42 offset0:12 offset1:28
	ds_read_b32 v42, v41 offset:64
	s_waitcnt lgkmcnt(0)
	v_mul_f32_e32 v36, v36, v42
	v_mul_f32_e32 v32, v32, v42
	v_add_u32_e32 v42, 0x4000, v40
	ds_write2_b32 v42, v36, v32 offset0:64 offset1:80
	ds_read_b32 v32, v41 offset:68
	s_waitcnt lgkmcnt(0)
	v_mul_f32_e32 v36, v37, v32
	v_mul_f32_e32 v32, v33, v32
	v_add_u32_e32 v33, 0x4400, v40
	ds_write2_b32 v33, v36, v32 offset0:68 offset1:84
	ds_read_b32 v32, v41 offset:72
	s_waitcnt lgkmcnt(0)
	v_mul_f32_e32 v33, v38, v32
	v_mul_f32_e32 v32, v34, v32
	v_add_u32_e32 v34, 0x4800, v40
	ds_write2_b32 v34, v33, v32 offset0:72 offset1:88
	ds_read_b32 v32, v41 offset:76
	v_add_u32_e32 v34, 0x4c00, v40
	s_waitcnt lgkmcnt(0)
	v_mul_f32_e32 v33, v39, v32
	v_mul_f32_e32 v32, v35, v32
	ds_write2_b32 v34, v33, v32 offset0:76 offset1:92
	ds_read_b32 v32, v41 offset:128
	s_waitcnt lgkmcnt(0)
	v_mul_f32_e32 v28, v28, v32
	v_mul_f32_e32 v24, v24, v32
	v_add_u32_e32 v32, 0x8000, v40
	ds_write2_b32 v32, v28, v24 offset0:128 offset1:144
	ds_read_b32 v24, v41 offset:132
	s_waitcnt lgkmcnt(0)
	v_mul_f32_e32 v28, v29, v24
	v_mul_f32_e32 v24, v25, v24
	v_add_u32_e32 v25, 0x8400, v40
	ds_write2_b32 v25, v28, v24 offset0:132 offset1:148
	ds_read_b32 v24, v41 offset:136
	s_waitcnt lgkmcnt(0)
	v_mul_f32_e32 v25, v30, v24
	v_mul_f32_e32 v24, v26, v24
	v_add_u32_e32 v26, 0x8800, v40
	ds_write2_b32 v26, v25, v24 offset0:136 offset1:152
	ds_read_b32 v24, v41 offset:140
	v_add_u32_e32 v26, 0x8c00, v40
	s_waitcnt lgkmcnt(0)
	v_mul_f32_e32 v25, v31, v24
	v_mul_f32_e32 v24, v27, v24
	ds_write2_b32 v26, v25, v24 offset0:140 offset1:156
	ds_read_b32 v24, v41 offset:192
	s_waitcnt lgkmcnt(0)
	v_mul_f32_e32 v20, v20, v24
	v_mul_f32_e32 v16, v16, v24
	v_add_u32_e32 v24, 0xc000, v40
	ds_write2_b32 v24, v20, v16 offset0:192 offset1:208
	ds_read_b32 v16, v41 offset:196
	s_waitcnt lgkmcnt(0)
	v_mul_f32_e32 v20, v21, v16
	v_mul_f32_e32 v16, v17, v16
	v_add_u32_e32 v17, 0xc400, v40
	ds_write2_b32 v17, v20, v16 offset0:196 offset1:212
	ds_read_b32 v16, v41 offset:200
	s_waitcnt lgkmcnt(0)
	v_mul_f32_e32 v17, v22, v16
	v_mul_f32_e32 v16, v18, v16
	v_add_u32_e32 v18, 0xc800, v40
	ds_write2_b32 v18, v17, v16 offset0:200 offset1:216
	ds_read_b32 v16, v41 offset:204
	v_add_u32_e32 v18, 0xcc00, v40
	s_waitcnt lgkmcnt(0)
	v_mul_f32_e32 v17, v23, v16
	v_mul_f32_e32 v16, v19, v16
	ds_write2_b32 v18, v17, v16 offset0:204 offset1:220
	v_mul_lo_u32 v16, v92, s4
	v_add3_u32 v52, 0, v16, v53
	s_waitcnt lgkmcnt(0)
	s_barrier
	ds_read_b128 v[44:47], v52
	ds_read_b128 v[40:43], v52 offset:16
	ds_read_b128 v[36:39], v52 offset:32
	ds_read_b128 v[32:35], v52 offset:48
	ds_read_b128 v[28:31], v52 offset:64
	ds_read_b128 v[24:27], v52 offset:80
	s_waitcnt lgkmcnt(5)
	v_mov_b32_e32 v18, v45
	s_waitcnt lgkmcnt(4)
	v_mov_b32_e32 v19, v41
	v_mov_b32_e32 v16, v44
	v_mov_b32_e32 v17, v40
	v_pk_mul_f32 v[18:19], v[18:19], v[18:19]
	s_mov_b32 s4, 0x800000
	v_pk_fma_f32 v[16:17], v[16:17], v[16:17], v[18:19]
	v_mov_b32_e32 v18, v46
	v_mov_b32_e32 v19, v42
	v_pk_fma_f32 v[16:17], v[18:19], v[18:19], v[16:17]
	v_mov_b32_e32 v18, v47
	v_mov_b32_e32 v19, v43
	v_pk_fma_f32 v[48:49], v[18:19], v[18:19], v[16:17]
	s_waitcnt lgkmcnt(3)
	v_mov_b32_e32 v18, v37
	s_waitcnt lgkmcnt(2)
	v_mov_b32_e32 v19, v33
	v_mov_b32_e32 v16, v36
	v_mov_b32_e32 v17, v32
	v_pk_mul_f32 v[18:19], v[18:19], v[18:19]
	v_add_f32_e32 v48, v48, v49
	v_pk_fma_f32 v[16:17], v[16:17], v[16:17], v[18:19]
	v_mov_b32_e32 v18, v38
	v_mov_b32_e32 v19, v34
	v_pk_fma_f32 v[16:17], v[18:19], v[18:19], v[16:17]
	v_mov_b32_e32 v18, v39
	v_mov_b32_e32 v19, v35
	v_pk_fma_f32 v[50:51], v[18:19], v[18:19], v[16:17]
	s_waitcnt lgkmcnt(1)
	v_mov_b32_e32 v18, v29
	s_waitcnt lgkmcnt(0)
	v_mov_b32_e32 v19, v25
	v_mov_b32_e32 v16, v28
	v_mov_b32_e32 v17, v24
	v_pk_mul_f32 v[18:19], v[18:19], v[18:19]
	v_add_f32_e32 v48, v48, v50
	v_pk_fma_f32 v[16:17], v[16:17], v[16:17], v[18:19]
	v_mov_b32_e32 v18, v30
	v_mov_b32_e32 v19, v26
	v_pk_fma_f32 v[16:17], v[18:19], v[18:19], v[16:17]
	v_mov_b32_e32 v18, v31
	v_mov_b32_e32 v19, v27
	v_pk_fma_f32 v[54:55], v[18:19], v[18:19], v[16:17]
	ds_read_b128 v[20:23], v52 offset:96
	ds_read_b128 v[16:19], v52 offset:112
	v_add_f32_e32 v48, v48, v51
	v_add_f32_e32 v48, v48, v54
	v_add_f32_e32 v48, v48, v55
	s_waitcnt lgkmcnt(1)
	v_mov_b32_e32 v58, v21
	s_waitcnt lgkmcnt(0)
	v_mov_b32_e32 v59, v17
	v_mov_b32_e32 v56, v20
	v_mov_b32_e32 v57, v16
	v_pk_mul_f32 v[58:59], v[58:59], v[58:59]
	s_nop 0
	v_pk_fma_f32 v[56:57], v[56:57], v[56:57], v[58:59]
	v_mov_b32_e32 v58, v22
	v_mov_b32_e32 v59, v18
	v_pk_fma_f32 v[56:57], v[58:59], v[58:59], v[56:57]
	v_mov_b32_e32 v58, v23
	v_mov_b32_e32 v59, v19
	v_pk_fma_f32 v[56:57], v[58:59], v[58:59], v[56:57]
	s_nop 0
	v_add_f32_e32 v48, v48, v56
	v_add_f32_e32 v48, v48, v57
	ds_bpermute_b32 v49, v78, v48
	s_waitcnt lgkmcnt(0)
	v_add_f32_e32 v48, v48, v49
	ds_bpermute_b32 v49, v79, v48
	s_waitcnt lgkmcnt(0)
	v_add_f32_e32 v48, v48, v49
	ds_bpermute_b32 v49, v97, v48
	s_waitcnt lgkmcnt(0)
	v_add_f32_e32 v48, v48, v49
	v_fmamk_f32 v48, v48, 0x3b800000, v91
	v_cmp_gt_f32_e32 vcc, s4, v48
	v_mul_f32_e32 v49, 0x4b800000, v48
	s_lshl_b32 s4, s40, 2
	v_cndmask_b32_e32 v48, v48, v49, vcc
	v_rsq_f32_e32 v48, v48
	s_add_u32 s4, s48, s4
	s_addc_u32 s5, s49, 0
	s_lshl_b32 s40, s40, 1
	v_mul_f32_e32 v49, 0x45800000, v48
	v_cndmask_b32_e32 v52, v48, v49, vcc
	v_lshlrev_b64 v[48:49], 12, v[74:75]
	v_lshl_add_u64 v[48:49], s[30:31], 0, v[48:49]
	v_lshl_add_u64 v[48:49], v[48:49], 0, s[40:41]
	v_lshl_add_u64 v[56:57], v[48:49], 0, v[72:73]
	v_lshlrev_b32_e32 v48, 16, v12
	v_and_b32_e32 v12, 0xffff0000, v12
	v_mul_f32_e32 v13, 0xbfb8aa3b, v48
	v_mul_f32_e32 v12, 0xbfb8aa3b, v12
	v_exp_f32_e32 v13, v13
	v_exp_f32_e32 v12, v12
	v_pk_mul_f32 v[44:45], v[44:45], v[52:53] op_sel_hi:[1,0]
	v_pk_mul_f32 v[46:47], v[46:47], v[52:53] op_sel_hi:[1,0]
	v_add_f32_e32 v13, 1.0, v13
	v_add_f32_e32 v12, 1.0, v12
	v_rcp_f32_e32 v58, v13
	v_rcp_f32_e32 v59, v12
	global_load_dwordx4 v[12:15], v53, s[4:5] offset:16
	global_load_dwordx4 v[48:51], v53, s[4:5]
	v_pk_mul_f32 v[40:41], v[40:41], v[52:53] op_sel_hi:[1,0]
	v_pk_mul_f32 v[42:43], v[42:43], v[52:53] op_sel_hi:[1,0]
	v_lshl_add_u64 v[54:55], v[56:57], 0, s[6:7]
	s_mov_b32 s6, 0x10e00000
	v_pk_mul_f32 v[36:37], v[36:37], v[52:53] op_sel_hi:[1,0]
	v_pk_mul_f32 v[38:39], v[38:39], v[52:53] op_sel_hi:[1,0]
	v_pk_mul_f32 v[32:33], v[32:33], v[52:53] op_sel_hi:[1,0]
	v_pk_mul_f32 v[34:35], v[34:35], v[52:53] op_sel_hi:[1,0]
	s_add_i32 s45, s45, s16
	s_add_i32 s14, s14, s15
	s_add_i32 s18, s18, s19
	s_add_u32 s33, s33, s22
	s_addc_u32 s35, s35, s23
	s_add_u32 s24, s24, s26
	s_addc_u32 s25, s25, s27
	s_add_u32 s36, s36, s38
	s_addc_u32 s37, s37, s39
	s_cmp_ge_i32 s45, s100
	s_waitcnt vmcnt(1)
	v_pk_mul_f32 v[12:13], v[12:13], v[40:41]
	s_waitcnt vmcnt(0)
	v_pk_mul_f32 v[44:45], v[48:49], v[44:45]
	v_mul_f32_e32 v48, 0xbfb8aa3b, v60
	v_mul_f32_e32 v49, 0xbfb8aa3b, v61
	v_exp_f32_e32 v48, v48
	v_exp_f32_e32 v49, v49
	v_pk_mul_f32 v[46:47], v[50:51], v[46:47]
	v_pk_mul_f32 v[14:15], v[14:15], v[42:43]
	v_add_f32_e32 v48, 1.0, v48
	v_add_f32_e32 v49, 1.0, v49
	v_rcp_f32_e32 v48, v48
	v_rcp_f32_e32 v49, v49
	v_pk_mul_f32 v[44:45], v[58:59], v[44:45]
	v_pk_mul_f32 v[46:47], v[48:49], v[46:47]
	v_mul_f32_e32 v48, 0xbfb8aa3b, v62
	v_mul_f32_e32 v49, 0xbfb8aa3b, v63
	v_exp_f32_e32 v48, v48
	v_exp_f32_e32 v49, v49
	v_add_f32_e32 v48, 1.0, v48
	v_add_f32_e32 v49, 1.0, v49
	v_rcp_f32_e32 v48, v48
	v_rcp_f32_e32 v49, v49
	s_nop 0
	v_pk_mul_f32 v[40:41], v[48:49], v[12:13]
	v_mul_f32_e32 v12, 0xbfb8aa3b, v64
	v_mul_f32_e32 v13, 0xbfb8aa3b, v65
	v_exp_f32_e32 v12, v12
	v_exp_f32_e32 v13, v13
	v_add_f32_e32 v12, 1.0, v12
	v_add_f32_e32 v13, 1.0, v13
	v_rcp_f32_e32 v12, v12
	v_rcp_f32_e32 v13, v13
	s_nop 0
	v_pk_mul_f32 v[42:43], v[12:13], v[14:15]
	v_cvt_pk_bf16_f32 v14, v40, v41
	v_add_co_u32_e32 v40, vcc, s6, v56
	v_cvt_pk_bf16_f32 v12, v44, v45
	v_cvt_pk_bf16_f32 v13, v46, v47
	v_cvt_pk_bf16_f32 v15, v42, v43
	v_addc_co_u32_e32 v41, vcc, 0, v57, vcc
	global_store_dwordx4 v[40:41], v[12:15], off offset:2048
	v_lshlrev_b32_e32 v42, 16, v9
	v_and_b32_e32 v43, 0xffff0000, v9
	v_lshlrev_b32_e32 v12, 16, v8
	v_and_b32_e32 v8, 0xffff0000, v8
	v_mul_f32_e32 v9, 0xbfb8aa3b, v12
	v_mul_f32_e32 v8, 0xbfb8aa3b, v8
	v_exp_f32_e32 v9, v9
	v_exp_f32_e32 v8, v8
	v_lshlrev_b32_e32 v44, 16, v10
	v_and_b32_e32 v45, 0xffff0000, v10
	v_add_f32_e32 v9, 1.0, v9
	v_add_f32_e32 v8, 1.0, v8
	v_lshlrev_b32_e32 v46, 16, v11
	v_and_b32_e32 v47, 0xffff0000, v11
	v_rcp_f32_e32 v40, v9
	v_rcp_f32_e32 v41, v8
	global_load_dwordx4 v[8:11], v53, s[4:5] offset:48
	global_load_dwordx4 v[12:15], v53, s[4:5] offset:32
	s_waitcnt vmcnt(1)
	v_pk_mul_f32 v[8:9], v[8:9], v[32:33]
	s_waitcnt vmcnt(0)
	v_pk_mul_f32 v[12:13], v[12:13], v[36:37]
	v_mul_f32_e32 v36, 0xbfb8aa3b, v42
	v_mul_f32_e32 v37, 0xbfb8aa3b, v43
	v_exp_f32_e32 v36, v36
	v_exp_f32_e32 v37, v37
	v_pk_mul_f32 v[14:15], v[14:15], v[38:39]
	v_pk_mul_f32 v[10:11], v[34:35], v[10:11]
	v_add_f32_e32 v36, 1.0, v36
	v_add_f32_e32 v37, 1.0, v37
	v_rcp_f32_e32 v36, v36
	v_rcp_f32_e32 v37, v37
	v_pk_mul_f32 v[12:13], v[40:41], v[12:13]
	v_pk_mul_f32 v[14:15], v[36:37], v[14:15]
	v_mul_f32_e32 v36, 0xbfb8aa3b, v44
	v_mul_f32_e32 v37, 0xbfb8aa3b, v45
	v_exp_f32_e32 v36, v36
	v_exp_f32_e32 v37, v37
	v_add_f32_e32 v36, 1.0, v36
	v_add_f32_e32 v37, 1.0, v37
	v_rcp_f32_e32 v36, v36
	v_rcp_f32_e32 v37, v37
	s_nop 0
	v_pk_mul_f32 v[32:33], v[36:37], v[8:9]
	v_mul_f32_e32 v8, 0xbfb8aa3b, v46
	v_mul_f32_e32 v9, 0xbfb8aa3b, v47
	v_exp_f32_e32 v8, v8
	v_exp_f32_e32 v9, v9
	v_lshlrev_b32_e32 v36, 16, v7
	v_and_b32_e32 v37, 0xffff0000, v7
	v_add_f32_e32 v8, 1.0, v8
	v_add_f32_e32 v9, 1.0, v9
	v_rcp_f32_e32 v8, v8
	v_rcp_f32_e32 v9, v9
	s_nop 0
	v_pk_mul_f32 v[34:35], v[8:9], v[10:11]
	v_cvt_pk_bf16_f32 v8, v12, v13
	v_cvt_pk_bf16_f32 v9, v14, v15
	v_cvt_pk_bf16_f32 v10, v32, v33
	v_cvt_pk_bf16_f32 v11, v34, v35
	global_store_dwordx4 v[54:55], v[8:11], off offset:16
	v_lshlrev_b32_e32 v32, 16, v5
	v_and_b32_e32 v33, 0xffff0000, v5
	v_lshlrev_b32_e32 v8, 16, v4
	v_and_b32_e32 v4, 0xffff0000, v4
	v_mul_f32_e32 v5, 0xbfb8aa3b, v8
	v_mul_f32_e32 v4, 0xbfb8aa3b, v4
	v_exp_f32_e32 v5, v5
	v_exp_f32_e32 v4, v4
	v_lshlrev_b32_e32 v34, 16, v6
	v_and_b32_e32 v35, 0xffff0000, v6
	v_add_f32_e32 v5, 1.0, v5
	v_add_f32_e32 v4, 1.0, v4
	v_rcp_f32_e32 v12, v5
	v_rcp_f32_e32 v13, v4
	global_load_dwordx4 v[4:7], v53, s[4:5] offset:80
	global_load_dwordx4 v[8:11], v53, s[4:5] offset:64
	v_pk_mul_f32 v[14:15], v[28:29], v[52:53] op_sel_hi:[1,0]
	s_waitcnt vmcnt(0)
	v_pk_mul_f32 v[8:9], v[14:15], v[8:9]
	s_nop 0
	v_pk_mul_f32 v[8:9], v[12:13], v[8:9]
	v_mul_f32_e32 v12, 0xbfb8aa3b, v32
	v_mul_f32_e32 v13, 0xbfb8aa3b, v33
	v_exp_f32_e32 v12, v12
	v_exp_f32_e32 v13, v13
	v_pk_mul_f32 v[14:15], v[30:31], v[52:53] op_sel_hi:[1,0]
	v_add_f32_e32 v12, 1.0, v12
	v_add_f32_e32 v13, 1.0, v13
	v_rcp_f32_e32 v12, v12
	v_rcp_f32_e32 v13, v13
	v_pk_mul_f32 v[10:11], v[14:15], v[10:11]
	v_pk_mul_f32 v[14:15], v[24:25], v[52:53] op_sel_hi:[1,0]
	v_lshlrev_b32_e32 v24, 16, v3
	v_pk_mul_f32 v[10:11], v[12:13], v[10:11]
	v_mul_f32_e32 v12, 0xbfb8aa3b, v34
	v_mul_f32_e32 v13, 0xbfb8aa3b, v35
	v_exp_f32_e32 v12, v12
	v_exp_f32_e32 v13, v13
	v_pk_mul_f32 v[4:5], v[14:15], v[4:5]
	v_pk_mul_f32 v[14:15], v[26:27], v[52:53] op_sel_hi:[1,0]
	v_add_f32_e32 v12, 1.0, v12
	v_add_f32_e32 v13, 1.0, v13
	v_rcp_f32_e32 v12, v12
	v_rcp_f32_e32 v13, v13
	v_pk_mul_f32 v[6:7], v[14:15], v[6:7]
	v_and_b32_e32 v25, 0xffff0000, v3
	v_pk_mul_f32 v[12:13], v[12:13], v[4:5]
	v_mul_f32_e32 v4, 0xbfb8aa3b, v36
	v_mul_f32_e32 v5, 0xbfb8aa3b, v37
	v_exp_f32_e32 v4, v4
	v_exp_f32_e32 v5, v5
	v_add_f32_e32 v4, 1.0, v4
	v_add_f32_e32 v5, 1.0, v5
	v_rcp_f32_e32 v4, v4
	v_rcp_f32_e32 v5, v5
	s_nop 0
	v_pk_mul_f32 v[14:15], v[4:5], v[6:7]
	v_cvt_pk_bf16_f32 v4, v8, v9
	v_cvt_pk_bf16_f32 v5, v10, v11
	v_cvt_pk_bf16_f32 v6, v12, v13
	v_cvt_pk_bf16_f32 v7, v14, v15
	global_store_dwordx4 v[54:55], v[4:7], off offset:32
	v_lshlrev_b32_e32 v12, 16, v1
	v_and_b32_e32 v13, 0xffff0000, v1
	v_lshlrev_b32_e32 v4, 16, v0
	v_and_b32_e32 v0, 0xffff0000, v0
	v_mul_f32_e32 v1, 0xbfb8aa3b, v4
	v_mul_f32_e32 v0, 0xbfb8aa3b, v0
	v_exp_f32_e32 v1, v1
	v_exp_f32_e32 v0, v0
	v_lshlrev_b32_e32 v14, 16, v2
	v_and_b32_e32 v15, 0xffff0000, v2
	v_add_f32_e32 v1, 1.0, v1
	v_add_f32_e32 v0, 1.0, v0
	v_rcp_f32_e32 v8, v1
	v_rcp_f32_e32 v9, v0
	global_load_dwordx4 v[0:3], v53, s[4:5] offset:112
	global_load_dwordx4 v[4:7], v53, s[4:5] offset:96
	v_pk_mul_f32 v[10:11], v[20:21], v[52:53] op_sel_hi:[1,0]
	s_waitcnt vmcnt(0)
	v_pk_mul_f32 v[4:5], v[10:11], v[4:5]
	s_nop 0
	v_pk_mul_f32 v[4:5], v[8:9], v[4:5]
	v_mul_f32_e32 v8, 0xbfb8aa3b, v12
	v_mul_f32_e32 v9, 0xbfb8aa3b, v13
	v_exp_f32_e32 v8, v8
	v_exp_f32_e32 v9, v9
	v_pk_mul_f32 v[10:11], v[22:23], v[52:53] op_sel_hi:[1,0]
	v_add_f32_e32 v8, 1.0, v8
	v_add_f32_e32 v9, 1.0, v9
	v_rcp_f32_e32 v8, v8
	v_rcp_f32_e32 v9, v9
	v_pk_mul_f32 v[6:7], v[10:11], v[6:7]
	v_pk_mul_f32 v[10:11], v[16:17], v[52:53] op_sel_hi:[1,0]
	v_pk_mul_f32 v[6:7], v[8:9], v[6:7]
	v_mul_f32_e32 v8, 0xbfb8aa3b, v14
	v_mul_f32_e32 v9, 0xbfb8aa3b, v15
	v_exp_f32_e32 v8, v8
	v_exp_f32_e32 v9, v9
	v_pk_mul_f32 v[0:1], v[10:11], v[0:1]
	v_pk_mul_f32 v[10:11], v[18:19], v[52:53] op_sel_hi:[1,0]
	v_add_f32_e32 v8, 1.0, v8
	v_add_f32_e32 v9, 1.0, v9
	v_rcp_f32_e32 v8, v8
	v_rcp_f32_e32 v9, v9
	v_pk_mul_f32 v[2:3], v[10:11], v[2:3]
	v_pk_mul_f32 v[8:9], v[8:9], v[0:1]
	v_mul_f32_e32 v0, 0xbfb8aa3b, v24
	v_mul_f32_e32 v1, 0xbfb8aa3b, v25
	v_exp_f32_e32 v0, v0
	v_exp_f32_e32 v1, v1
	v_add_f32_e32 v0, 1.0, v0
	v_add_f32_e32 v1, 1.0, v1
	v_rcp_f32_e32 v0, v0
	v_rcp_f32_e32 v1, v1
	s_nop 0
	v_pk_mul_f32 v[10:11], v[0:1], v[2:3]
	v_cvt_pk_bf16_f32 v0, v4, v5
	v_cvt_pk_bf16_f32 v1, v6, v7
	v_cvt_pk_bf16_f32 v2, v8, v9
	v_cvt_pk_bf16_f32 v3, v10, v11
	global_store_dwordx4 v[54:55], v[0:3], off offset:48
	s_barrier
	s_cbranch_scc1 .LBB0_662

.LBB0_662:
	s_sub_i32 s68, s2, 32
	v_readlane_b32 s16, v239, 2
	s_nop 0
	s_sub_i32 s16, s16, 32
	v_readlane_b32 s4, v238, 31
	v_readlane_b32 s5, v238, 32
	s_and_b64 s[4:5], s[4:5], exec
	s_cselect_b32 s8, 0xc0, 64
	s_cmp_ge_i32 s68, s8
	s_cselect_b64 s[4:5], -1, 0
	s_or_b32 s6, s8, 32
	s_cmp_lt_i32 s68, s6
	s_cselect_b64 s[6:7], -1, 0
	s_and_b64 s[4:5], s[4:5], s[6:7]
	s_and_b64 vcc, exec, s[4:5]
	s_cbranch_vccz .LBB0_701
	s_mov_b64 s[4:5], exec
	v_readlane_b32 s6, v239, 4
	v_readlane_b32 s7, v239, 5
	s_and_b64 s[6:7], s[4:5], s[6:7]
	s_mov_b64 exec, s[6:7]
	s_cbranch_execz .LBB0_678
	s_mov_b32 s9, 0x100000
	v_mov_b32_e32 v0, 0
	s_branch .LBB0_667

.LBB0_747:
	s_or_b64 exec, exec, s[36:37]
	v_lshl_add_u64 v[16:17], s[30:31], 0, v[152:153]
	s_mov_b64 s[34:35], 0xe1800
	v_lshl_add_u64 v[18:19], v[16:17], 0, s[34:35]
	v_add_co_u32_e32 v16, vcc, 0xe1000, v16
	v_cvt_pk_bf16_f32 v116, v52, v53
	s_nop 0
	v_addc_co_u32_e32 v17, vcc, 0, v17, vcc
	global_load_dwordx4 v[24:27], v[16:17], off offset:2048
	s_nop 0
	global_load_dwordx4 v[16:19], v[18:19], off offset:16
	v_mov_b32_e32 v204, s24
	ds_read_b32 v174, v204
	ds_read2_b64 v[244:247], v187 offset1:4
	v_add_u32_e32 v199, 0x4000, v187
	ds_read2_b64 v[248:251], v199 offset0:128 offset1:132
	ds_read2_b64 v[252:255], v187 offset0:8 offset1:12
	ds_read2_b64 v[200:203], v199 offset0:136 offset1:140
	v_cvt_pk_bf16_f32 v116, v52, v53
	v_cvt_pk_bf16_f32 v117, v54, v55
	v_cvt_pk_bf16_f32 v118, v48, v49
	v_cvt_pk_bf16_f32 v119, v50, v51
	v_cvt_pk_bf16_f32 v112, v44, v45
	v_cvt_pk_bf16_f32 v113, v46, v47
	v_cvt_pk_bf16_f32 v114, v20, v21
	v_cvt_pk_bf16_f32 v115, v22, v23
	v_cvt_pk_bf16_f32 v108, v40, v41
	v_cvt_pk_bf16_f32 v109, v42, v43
	v_cvt_pk_bf16_f32 v110, v36, v37
	v_cvt_pk_bf16_f32 v111, v38, v39
	v_cvt_pk_bf16_f32 v104, v32, v33
	v_cvt_pk_bf16_f32 v105, v34, v35
	v_cvt_pk_bf16_f32 v106, v28, v29
	v_cvt_pk_bf16_f32 v107, v30, v31
	s_mov_b64 s[34:35], 0xe0000
	v_lshl_add_u64 v[152:153], v[152:153], 0, s[34:35]
	v_lshl_add_u64 v[154:155], v[154:155], 0, s[26:27]
	v_lshl_add_u64 v[156:157], v[156:157], 0, s[26:27]
	v_lshl_add_u64 v[158:159], v[158:159], 0, s[26:27]
	v_lshl_add_u64 v[160:161], v[160:161], 0, s[26:27]
	v_lshl_add_u64 v[162:163], v[162:163], 0, s[26:27]
	v_lshl_add_u64 v[164:165], v[164:165], 0, s[26:27]
	v_lshl_add_u64 v[166:167], v[166:167], 0, s[26:27]
	v_lshl_add_u64 v[168:169], v[168:169], 0, s[26:27]
	v_lshl_add_u64 v[170:171], v[170:171], 0, s[26:27]
	v_lshl_add_u64 v[172:173], v[172:173], 0, s[26:27]
	s_waitcnt lgkmcnt(3)
	v_mfma_f32_16x16x32_bf16 v[120:123], v[244:247], v[116:119], 0
	ds_read2_b64 v[244:247], v187 offset0:16 offset1:20
	s_waitcnt lgkmcnt(3)
	v_mfma_f32_16x16x32_bf16 v[136:139], v[248:251], v[116:119], 0
	ds_read2_b64 v[248:251], v199 offset0:144 offset1:148
	s_waitcnt lgkmcnt(3)
	v_mfma_f32_16x16x32_bf16 v[120:123], v[252:255], v[112:115], v[120:123]
	ds_read2_b64 v[252:255], v187 offset0:24 offset1:28
	v_pk_mul_f32 v[52:53], v[52:53], v[174:175] op_sel_hi:[1,0]
	v_pk_mul_f32 v[54:55], v[54:55], v[174:175] op_sel_hi:[1,0]
	s_waitcnt lgkmcnt(3)
	v_mfma_f32_16x16x32_bf16 v[136:139], v[200:203], v[112:115], v[136:139]
	ds_read2_b64 v[200:203], v199 offset0:152 offset1:156
	v_pk_mul_f32 v[48:49], v[48:49], v[174:175] op_sel_hi:[1,0]
	s_waitcnt lgkmcnt(3)
	v_mfma_f32_16x16x32_bf16 v[120:123], v[244:247], v[108:111], v[120:123]
	v_add_u32_e32 v204, 0x1000, v187
	ds_read2_b64 v[244:247], v204 offset0:32 offset1:36
	v_pk_mul_f32 v[50:51], v[50:51], v[174:175] op_sel_hi:[1,0]
	v_pk_mul_f32 v[44:45], v[44:45], v[174:175] op_sel_hi:[1,0]
	s_waitcnt lgkmcnt(3)
	v_mfma_f32_16x16x32_bf16 v[136:139], v[248:251], v[108:111], v[136:139]
	v_add_u32_e32 v199, 0x5000, v187
	ds_read2_b64 v[248:251], v199 offset0:160 offset1:164
	v_pk_mul_f32 v[46:47], v[46:47], v[174:175] op_sel_hi:[1,0]
	s_waitcnt lgkmcnt(3)
	v_mfma_f32_16x16x32_bf16 v[120:123], v[252:255], v[104:107], v[120:123]
	ds_read2_b64 v[252:255], v204 offset0:40 offset1:44
	v_pk_mul_f32 v[20:21], v[20:21], v[174:175] op_sel_hi:[1,0]
	v_pk_mul_f32 v[22:23], v[22:23], v[174:175] op_sel_hi:[1,0]
	s_waitcnt lgkmcnt(3)
	v_mfma_f32_16x16x32_bf16 v[136:139], v[200:203], v[104:107], v[136:139]
	ds_read2_b64 v[200:203], v199 offset0:168 offset1:172
	v_pk_mul_f32 v[40:41], v[40:41], v[174:175] op_sel_hi:[1,0]
	s_waitcnt lgkmcnt(3)
	v_mfma_f32_16x16x32_bf16 v[124:127], v[244:247], v[116:119], 0
	ds_read2_b64 v[244:247], v204 offset0:48 offset1:52
	v_pk_mul_f32 v[42:43], v[42:43], v[174:175] op_sel_hi:[1,0]
	v_pk_mul_f32 v[36:37], v[36:37], v[174:175] op_sel_hi:[1,0]
	s_waitcnt lgkmcnt(3)
	v_mfma_f32_16x16x32_bf16 v[140:143], v[248:251], v[116:119], 0
	ds_read2_b64 v[248:251], v199 offset0:176 offset1:180
	v_pk_mul_f32 v[38:39], v[38:39], v[174:175] op_sel_hi:[1,0]
	s_waitcnt lgkmcnt(3)
	v_mfma_f32_16x16x32_bf16 v[124:127], v[252:255], v[112:115], v[124:127]
	ds_read2_b64 v[252:255], v204 offset0:56 offset1:60
	v_pk_mul_f32 v[32:33], v[32:33], v[174:175] op_sel_hi:[1,0]
	v_pk_mul_f32 v[34:35], v[34:35], v[174:175] op_sel_hi:[1,0]
	s_waitcnt lgkmcnt(3)
	v_mfma_f32_16x16x32_bf16 v[140:143], v[200:203], v[112:115], v[140:143]
	ds_read2_b64 v[200:203], v199 offset0:184 offset1:188
	v_pk_mul_f32 v[28:29], v[28:29], v[174:175] op_sel_hi:[1,0]
	s_waitcnt lgkmcnt(3)
	v_mfma_f32_16x16x32_bf16 v[124:127], v[244:247], v[108:111], v[124:127]
	v_add_u32_e32 v204, 0x2000, v187
	ds_read2_b64 v[244:247], v204 offset0:64 offset1:68
	v_pk_mul_f32 v[30:31], v[30:31], v[174:175] op_sel_hi:[1,0]
	s_waitcnt lgkmcnt(3)
	v_mfma_f32_16x16x32_bf16 v[140:143], v[248:251], v[108:111], v[140:143]
	v_add_u32_e32 v199, 0x6000, v187
	ds_read2_b64 v[248:251], v199 offset0:192 offset1:196
	s_waitcnt lgkmcnt(3)
	v_mfma_f32_16x16x32_bf16 v[124:127], v[252:255], v[104:107], v[124:127]
	ds_read2_b64 v[252:255], v204 offset0:72 offset1:76
	s_waitcnt lgkmcnt(3)
	v_mfma_f32_16x16x32_bf16 v[140:143], v[200:203], v[104:107], v[140:143]
	ds_read2_b64 v[200:203], v199 offset0:200 offset1:204
	s_waitcnt lgkmcnt(3)
	v_mfma_f32_16x16x32_bf16 v[128:131], v[244:247], v[116:119], 0
	ds_read2_b64 v[244:247], v204 offset0:80 offset1:84
	s_waitcnt lgkmcnt(3)
	v_mfma_f32_16x16x32_bf16 v[144:147], v[248:251], v[116:119], 0
	ds_read2_b64 v[248:251], v199 offset0:208 offset1:212
	s_waitcnt lgkmcnt(3)
	v_mfma_f32_16x16x32_bf16 v[128:131], v[252:255], v[112:115], v[128:131]
	ds_read2_b64 v[252:255], v204 offset0:88 offset1:92
	s_waitcnt lgkmcnt(3)
	v_mfma_f32_16x16x32_bf16 v[144:147], v[200:203], v[112:115], v[144:147]
	ds_read2_b64 v[200:203], v199 offset0:216 offset1:220
	s_waitcnt lgkmcnt(3)
	v_mfma_f32_16x16x32_bf16 v[128:131], v[244:247], v[108:111], v[128:131]
	v_add_u32_e32 v204, 0x3000, v187
	ds_read2_b64 v[244:247], v204 offset0:96 offset1:100
	s_waitcnt lgkmcnt(3)
	v_mfma_f32_16x16x32_bf16 v[144:147], v[248:251], v[108:111], v[144:147]
	v_add_u32_e32 v199, 0x7000, v187
	ds_read2_b64 v[248:251], v199 offset0:224 offset1:228
	s_waitcnt lgkmcnt(3)
	v_mfma_f32_16x16x32_bf16 v[128:131], v[252:255], v[104:107], v[128:131]
	ds_read2_b64 v[252:255], v204 offset0:104 offset1:108
	s_waitcnt lgkmcnt(3)
	v_mfma_f32_16x16x32_bf16 v[144:147], v[200:203], v[104:107], v[144:147]
	ds_read2_b64 v[200:203], v199 offset0:232 offset1:236
	s_waitcnt lgkmcnt(3)
	v_mfma_f32_16x16x32_bf16 v[132:135], v[244:247], v[116:119], 0
	ds_read2_b64 v[244:247], v204 offset0:112 offset1:116
	s_waitcnt lgkmcnt(3)
	v_mfma_f32_16x16x32_bf16 v[240:243], v[248:251], v[116:119], 0
	ds_read2_b64 v[248:251], v199 offset0:240 offset1:244
	s_waitcnt lgkmcnt(3)
	v_mfma_f32_16x16x32_bf16 v[132:135], v[252:255], v[112:115], v[132:135]
	ds_read2_b64 v[252:255], v204 offset0:120 offset1:124
	s_waitcnt lgkmcnt(3)
	v_mfma_f32_16x16x32_bf16 v[240:243], v[200:203], v[112:115], v[240:243]
	ds_read2_b64 v[200:203], v199 offset0:248 offset1:252
	s_waitcnt lgkmcnt(3)
	v_mfma_f32_16x16x32_bf16 v[132:135], v[244:247], v[108:111], v[132:135]
	v_add_u32_e32 v204, 0xf000, v186
	ds_read2_b64 v[244:247], v204 offset0:128 offset1:132
	s_waitcnt lgkmcnt(3)
	v_mfma_f32_16x16x32_bf16 v[240:243], v[248:251], v[108:111], v[240:243]
	ds_read2_b64 v[248:251], v204 offset0:136 offset1:140
	s_waitcnt lgkmcnt(3)
	v_mfma_f32_16x16x32_bf16 v[132:135], v[252:255], v[104:107], v[132:135]
	v_add_u32_e32 v199, 0x8800, v185
	ds_read2_b64 v[252:255], v199 offset1:4
	s_waitcnt lgkmcnt(3)
	v_mfma_f32_16x16x32_bf16 v[240:243], v[200:203], v[104:107], v[240:243]
	ds_read2_b64 v[200:203], v199 offset0:8 offset1:12
	s_waitcnt lgkmcnt(3)
	v_lshlrev_b32_e32 v104, 16, v244
	v_and_b32_e32 v105, 0xffff0000, v244
	v_lshlrev_b32_e32 v106, 16, v245
	v_and_b32_e32 v107, 0xffff0000, v245
	v_pk_add_f32 v[120:121], v[104:105], v[120:121] neg_lo:[0,1] neg_hi:[0,1]
	v_pk_add_f32 v[122:123], v[106:107], v[122:123] neg_lo:[0,1] neg_hi:[0,1]
	v_lshlrev_b32_e32 v108, 16, v246
	v_and_b32_e32 v109, 0xffff0000, v246
	v_lshlrev_b32_e32 v110, 16, v247
	v_and_b32_e32 v111, 0xffff0000, v247
	v_pk_add_f32 v[124:125], v[108:109], v[124:125] neg_lo:[0,1] neg_hi:[0,1]
	v_pk_add_f32 v[126:127], v[110:111], v[126:127] neg_lo:[0,1] neg_hi:[0,1]
	v_add_u32_e32 v204, 0x9000, v185
	ds_read2_b64 v[244:247], v204 offset0:32 offset1:36
	v_cvt_pk_bf16_f32 v116, v120, v121
	v_cvt_pk_bf16_f32 v117, v122, v123
	v_cvt_pk_bf16_f32 v118, v124, v125
	v_cvt_pk_bf16_f32 v119, v126, v127
	s_waitcnt lgkmcnt(3)
	v_lshlrev_b32_e32 v104, 16, v248
	v_and_b32_e32 v105, 0xffff0000, v248
	v_lshlrev_b32_e32 v106, 16, v249
	v_and_b32_e32 v107, 0xffff0000, v249
	v_pk_add_f32 v[128:129], v[104:105], v[128:129] neg_lo:[0,1] neg_hi:[0,1]
	v_pk_add_f32 v[130:131], v[106:107], v[130:131] neg_lo:[0,1] neg_hi:[0,1]
	v_lshlrev_b32_e32 v108, 16, v250
	v_and_b32_e32 v109, 0xffff0000, v250
	v_lshlrev_b32_e32 v110, 16, v251
	v_and_b32_e32 v111, 0xffff0000, v251
	v_pk_add_f32 v[132:133], v[108:109], v[132:133] neg_lo:[0,1] neg_hi:[0,1]
	v_pk_add_f32 v[134:135], v[110:111], v[134:135] neg_lo:[0,1] neg_hi:[0,1]
	ds_read2_b64 v[248:251], v204 offset0:40 offset1:44
	v_cvt_pk_bf16_f32 v112, v128, v129
	v_cvt_pk_bf16_f32 v113, v130, v131
	v_cvt_pk_bf16_f32 v114, v132, v133
	v_cvt_pk_bf16_f32 v115, v134, v135
	s_waitcnt lgkmcnt(3)
	s_nop 1
	v_mfma_f32_16x16x32_bf16 v[136:139], v[252:255], v[116:119], v[136:139]
	v_add_u32_e32 v199, 0x9800, v185
	ds_read2_b64 v[252:255], v199 offset0:64 offset1:68
	s_waitcnt lgkmcnt(3)
	v_mfma_f32_16x16x32_bf16 v[136:139], v[200:203], v[112:115], v[136:139]
	ds_read2_b64 v[200:203], v199 offset0:72 offset1:76
	s_waitcnt lgkmcnt(3)
	v_mfma_f32_16x16x32_bf16 v[140:143], v[244:247], v[116:119], v[140:143]
	v_add_u32_e32 v204, 0xa000, v185
	ds_read2_b64 v[244:247], v204 offset0:96 offset1:100
	s_waitcnt lgkmcnt(3)
	v_mfma_f32_16x16x32_bf16 v[140:143], v[248:251], v[112:115], v[140:143]
	ds_read2_b64 v[248:251], v204 offset0:104 offset1:108
	s_waitcnt lgkmcnt(3)
	v_mfma_f32_16x16x32_bf16 v[144:147], v[252:255], v[116:119], v[144:147]
	v_add_u32_e32 v199, 0xa800, v185
	ds_read2_b64 v[252:255], v199 offset0:128 offset1:132
	s_waitcnt lgkmcnt(3)
	v_mfma_f32_16x16x32_bf16 v[144:147], v[200:203], v[112:115], v[144:147]
	ds_read2_b64 v[200:203], v199 offset0:136 offset1:140
	s_waitcnt lgkmcnt(3)
	v_mfma_f32_16x16x32_bf16 v[240:243], v[244:247], v[116:119], v[240:243]
	v_add_u32_e32 v204, 0xb000, v185
	ds_read2_b64 v[244:247], v204 offset0:160 offset1:164
	s_waitcnt lgkmcnt(3)
	v_mfma_f32_16x16x32_bf16 v[240:243], v[248:251], v[112:115], v[240:243]
	ds_read2_b64 v[248:251], v204 offset0:168 offset1:172
	s_waitcnt lgkmcnt(3)
	v_mfma_f32_16x16x32_bf16 v[52:55], v[252:255], v[116:119], v[52:55]
	v_add_u32_e32 v199, 0xb800, v185
	ds_read2_b64 v[252:255], v199 offset0:192 offset1:196
	s_waitcnt lgkmcnt(3)
	v_mfma_f32_16x16x32_bf16 v[52:55], v[200:203], v[112:115], v[52:55]
	ds_read2_b64 v[200:203], v199 offset0:200 offset1:204
	s_waitcnt lgkmcnt(3)
	v_mfma_f32_16x16x32_bf16 v[48:51], v[244:247], v[116:119], v[48:51]
	v_add_u32_e32 v204, 0xc000, v185
	ds_read2_b64 v[244:247], v204 offset0:224 offset1:228
	s_waitcnt lgkmcnt(3)
	v_mfma_f32_16x16x32_bf16 v[48:51], v[248:251], v[112:115], v[48:51]
	ds_read2_b64 v[248:251], v204 offset0:232 offset1:236
	s_waitcnt lgkmcnt(3)
	v_mfma_f32_16x16x32_bf16 v[44:47], v[252:255], v[116:119], v[44:47]
	v_add_u32_e32 v199, 0xd000, v185
	ds_read2_b64 v[252:255], v199 offset1:4
	s_waitcnt lgkmcnt(3)
	v_mfma_f32_16x16x32_bf16 v[44:47], v[200:203], v[112:115], v[44:47]
	ds_read2_b64 v[200:203], v199 offset0:8 offset1:12
	s_waitcnt lgkmcnt(3)
	v_mfma_f32_16x16x32_bf16 v[20:23], v[244:247], v[116:119], v[20:23]
	v_add_u32_e32 v204, 0xd800, v185
	ds_read2_b64 v[244:247], v204 offset0:32 offset1:36
	s_waitcnt lgkmcnt(3)
	v_mfma_f32_16x16x32_bf16 v[20:23], v[248:251], v[112:115], v[20:23]
	ds_read2_b64 v[248:251], v204 offset0:40 offset1:44
	s_waitcnt lgkmcnt(3)
	v_mfma_f32_16x16x32_bf16 v[40:43], v[252:255], v[116:119], v[40:43]
	v_add_u32_e32 v199, 0xe000, v185
	ds_read2_b64 v[252:255], v199 offset0:64 offset1:68
	s_waitcnt lgkmcnt(3)
	v_mfma_f32_16x16x32_bf16 v[40:43], v[200:203], v[112:115], v[40:43]
	ds_read2_b64 v[200:203], v199 offset0:72 offset1:76
	s_waitcnt lgkmcnt(3)
	v_mfma_f32_16x16x32_bf16 v[36:39], v[244:247], v[116:119], v[36:39]
	v_add_u32_e32 v204, 0xe800, v185
	ds_read2_b64 v[244:247], v204 offset0:96 offset1:100
	s_waitcnt lgkmcnt(3)
	v_mfma_f32_16x16x32_bf16 v[36:39], v[248:251], v[112:115], v[36:39]
	ds_read2_b64 v[248:251], v204 offset0:104 offset1:108
	s_waitcnt lgkmcnt(3)
	v_mfma_f32_16x16x32_bf16 v[32:35], v[252:255], v[116:119], v[32:35]
	s_waitcnt lgkmcnt(2)
	v_mfma_f32_16x16x32_bf16 v[32:35], v[200:203], v[112:115], v[32:35]
	s_waitcnt lgkmcnt(1)
	v_mfma_f32_16x16x32_bf16 v[28:31], v[244:247], v[116:119], v[28:31]
	s_waitcnt lgkmcnt(0)
	v_mfma_f32_16x16x32_bf16 v[28:31], v[248:251], v[112:115], v[28:31]
	ds_write2_b32 v149, v136, v137 offset1:132
	v_add_u32_e32 v199, 0x400, v149
	ds_write2_b32 v199, v138, v139 offset0:8 offset1:140
	v_add_u32_e32 v199, 0x2000, v149
	ds_write2_b32 v199, v140, v141 offset0:64 offset1:196
	v_add_u32_e32 v199, 0x2400, v149
	ds_write2_b32 v199, v142, v143 offset0:72 offset1:204
	v_add_u32_e32 v199, 0x4200, v149
	ds_write2_b32 v199, v144, v145 offset1:132
	v_add_u32_e32 v199, 0x4600, v149
	ds_write2_b32 v199, v146, v147 offset0:8 offset1:140
	v_add_u32_e32 v199, 0x6200, v149
	ds_write2_b32 v199, v240, v241 offset0:64 offset1:196
	v_add_u32_e32 v199, 0x6600, v149
	ds_write2_b32 v199, v242, v243 offset0:72 offset1:204
	s_waitcnt lgkmcnt(0)
	s_barrier
	ds_read_b128 v[118:121], v184
	ds_read_b128 v[112:115], v184 offset:16
	ds_read_b128 v[108:111], v184 offset:32
	ds_read_b128 v[104:107], v184 offset:48
	s_waitcnt lgkmcnt(3)
	v_mov_b32_e32 v122, v119
	s_waitcnt lgkmcnt(2)
	v_mov_b32_e32 v123, v113
	v_mov_b32_e32 v116, v118
	v_mov_b32_e32 v117, v112
	v_pk_mul_f32 v[122:123], v[122:123], v[122:123]
	s_waitcnt lgkmcnt(1)
	v_mov_b32_e32 v124, v109
	v_pk_fma_f32 v[116:117], v[116:117], v[116:117], v[122:123]
	v_mov_b32_e32 v122, v120
	v_mov_b32_e32 v123, v114
	v_pk_fma_f32 v[116:117], v[122:123], v[122:123], v[116:117]
	v_mov_b32_e32 v122, v121
	v_mov_b32_e32 v123, v115
	s_waitcnt lgkmcnt(0)
	v_mov_b32_e32 v125, v105
	v_pk_fma_f32 v[116:117], v[122:123], v[122:123], v[116:117]
	v_mov_b32_e32 v122, v108
	v_mov_b32_e32 v123, v104
	v_pk_mul_f32 v[124:125], v[124:125], v[124:125]
	v_add_f32_e32 v116, v116, v117
	v_pk_fma_f32 v[122:123], v[122:123], v[122:123], v[124:125]
	v_mov_b32_e32 v124, v110
	v_mov_b32_e32 v125, v106
	v_pk_fma_f32 v[122:123], v[124:125], v[124:125], v[122:123]
	v_mov_b32_e32 v124, v111
	v_mov_b32_e32 v125, v107
	v_pk_fma_f32 v[122:123], v[124:125], v[124:125], v[122:123]
	s_nop 0
	v_add_f32_e32 v116, v116, v122
	v_add_f32_e32 v116, v116, v123
	ds_bpermute_b32 v117, v183, v116
	s_waitcnt vmcnt(7)
	v_lshlrev_b32_e32 v122, 16, v100
	v_and_b32_e32 v123, 0xffff0000, v100
	v_mul_f32_e32 v100, 0xbfb8aa3b, v122
	v_exp_f32_e32 v100, v100
	s_waitcnt lgkmcnt(0)
	v_add_f32_e32 v116, v116, v117
	ds_bpermute_b32 v117, v182, v116
	v_add_f32_e32 v100, 1.0, v100
	v_rcp_f32_e32 v124, v100
	v_mul_f32_e32 v100, 0xbfb8aa3b, v123
	s_waitcnt lgkmcnt(0)
	v_add_f32_e32 v116, v116, v117
	ds_bpermute_b32 v117, v177, v116
	v_exp_f32_e32 v100, v100
	s_waitcnt lgkmcnt(0)
	v_add_f32_e32 v116, v116, v117
	v_fmamk_f32 v116, v116, 0x3c000000, v198
	v_cmp_gt_f32_e32 vcc, s33, v116
	v_mul_f32_e32 v117, 0x4b800000, v116
	v_add_f32_e32 v100, 1.0, v100
	v_cndmask_b32_e32 v116, v116, v117, vcc
	v_rsq_f32_e32 v116, v116
	v_rcp_f32_e32 v125, v100
	v_lshlrev_b32_e32 v100, 16, v101
	v_and_b32_e32 v101, 0xffff0000, v101
	v_mul_f32_e32 v117, 0x45800000, v116
	v_cndmask_b32_e32 v116, v116, v117, vcc
	v_pk_mul_f32 v[118:119], v[118:119], v[116:117] op_sel_hi:[1,0]
	v_mul_f32_e32 v117, 0xbfb8aa3b, v100
	v_exp_f32_e32 v117, v117
	s_waitcnt vmcnt(5)
	v_pk_mul_f32 v[118:119], v[12:13], v[118:119]
	v_pk_mul_f32 v[122:123], v[124:125], v[122:123]
	v_add_f32_e32 v117, 1.0, v117
	v_pk_mul_f32 v[118:119], v[122:123], v[118:119]
	v_rcp_f32_e32 v122, v117
	v_pk_mul_f32 v[120:121], v[120:121], v[116:117] op_sel_hi:[1,0]
	v_mul_f32_e32 v117, 0xbfb8aa3b, v101
	v_exp_f32_e32 v117, v117
	v_pk_mul_f32 v[120:121], v[14:15], v[120:121]
	v_add_f32_e32 v117, 1.0, v117
	v_rcp_f32_e32 v123, v117
	v_pk_mul_f32 v[112:113], v[112:113], v[116:117] op_sel_hi:[1,0]
	v_pk_mul_f32 v[100:101], v[122:123], v[100:101]
	s_nop 0
	v_pk_mul_f32 v[100:101], v[100:101], v[120:121]
	v_lshlrev_b32_e32 v120, 16, v102
	v_and_b32_e32 v121, 0xffff0000, v102
	v_mul_f32_e32 v102, 0xbfb8aa3b, v120
	v_exp_f32_e32 v102, v102
	s_waitcnt vmcnt(4)
	v_pk_mul_f32 v[112:113], v[8:9], v[112:113]
	v_add_f32_e32 v102, 1.0, v102
	v_rcp_f32_e32 v122, v102
	v_mul_f32_e32 v102, 0xbfb8aa3b, v121
	v_exp_f32_e32 v102, v102
	s_nop 0
	v_add_f32_e32 v102, 1.0, v102
	v_rcp_f32_e32 v123, v102
	v_lshlrev_b32_e32 v102, 16, v103
	v_mul_f32_e32 v117, 0xbfb8aa3b, v102
	v_exp_f32_e32 v117, v117
	v_pk_mul_f32 v[120:121], v[122:123], v[120:121]
	v_and_b32_e32 v103, 0xffff0000, v103
	v_pk_mul_f32 v[112:113], v[120:121], v[112:113]
	v_add_f32_e32 v117, 1.0, v117
	v_rcp_f32_e32 v120, v117
	v_pk_mul_f32 v[114:115], v[114:115], v[116:117] op_sel_hi:[1,0]
	v_mul_f32_e32 v117, 0xbfb8aa3b, v103
	v_exp_f32_e32 v117, v117
	v_pk_mul_f32 v[114:115], v[10:11], v[114:115]
	v_add_f32_e32 v117, 1.0, v117
	v_rcp_f32_e32 v121, v117
	v_pk_mul_f32 v[108:109], v[108:109], v[116:117] op_sel_hi:[1,0]
	v_pk_mul_f32 v[110:111], v[110:111], v[116:117] op_sel_hi:[1,0]
	s_waitcnt vmcnt(3)
	v_pk_mul_f32 v[108:109], v[4:5], v[108:109]
	v_pk_mul_f32 v[102:103], v[120:121], v[102:103]
	v_pk_mul_f32 v[110:111], v[6:7], v[110:111]
	v_pk_mul_f32 v[102:103], v[102:103], v[114:115]
	v_lshlrev_b32_e32 v114, 16, v96
	v_and_b32_e32 v115, 0xffff0000, v96
	v_mul_f32_e32 v96, 0xbfb8aa3b, v114
	v_exp_f32_e32 v96, v96
	v_pk_mul_f32 v[104:105], v[104:105], v[116:117] op_sel_hi:[1,0]
	v_pk_mul_f32 v[106:107], v[106:107], v[116:117] op_sel_hi:[1,0]
	s_waitcnt vmcnt(2)
	v_pk_mul_f32 v[104:105], v[0:1], v[104:105]
	v_add_f32_e32 v96, 1.0, v96
	v_rcp_f32_e32 v120, v96
	v_mul_f32_e32 v96, 0xbfb8aa3b, v115
	v_exp_f32_e32 v96, v96
	v_pk_mul_f32 v[106:107], v[2:3], v[106:107]
	v_add_f32_e32 v96, 1.0, v96
	v_rcp_f32_e32 v121, v96
	v_lshlrev_b32_e32 v96, 16, v97
	v_and_b32_e32 v97, 0xffff0000, v97
	v_pk_mul_f32 v[114:115], v[120:121], v[114:115]
	s_nop 0
	v_pk_mul_f32 v[108:109], v[114:115], v[108:109]
	v_mul_f32_e32 v114, 0xbfb8aa3b, v96
	v_mul_f32_e32 v115, 0xbfb8aa3b, v97
	v_exp_f32_e32 v114, v114
	v_exp_f32_e32 v115, v115
	v_add_f32_e32 v114, 1.0, v114
	v_add_f32_e32 v115, 1.0, v115
	v_rcp_f32_e32 v114, v114
	v_rcp_f32_e32 v115, v115
	s_nop 0
	v_pk_mul_f32 v[96:97], v[114:115], v[96:97]
	s_nop 0
	v_pk_mul_f32 v[110:111], v[96:97], v[110:111]
	v_lshlrev_b32_e32 v96, 16, v98
	v_and_b32_e32 v97, 0xffff0000, v98
	v_mul_f32_e32 v98, 0xbfb8aa3b, v96
	v_exp_f32_e32 v98, v98
	s_nop 0
	v_add_f32_e32 v98, 1.0, v98
	v_rcp_f32_e32 v114, v98
	v_mul_f32_e32 v98, 0xbfb8aa3b, v97
	v_exp_f32_e32 v98, v98
	s_nop 0
	v_add_f32_e32 v98, 1.0, v98
	v_rcp_f32_e32 v115, v98
	s_nop 0
	v_pk_mul_f32 v[96:97], v[114:115], v[96:97]
	s_nop 0
	v_pk_mul_f32 v[104:105], v[96:97], v[104:105]
	v_lshlrev_b32_e32 v96, 16, v99
	v_and_b32_e32 v97, 0xffff0000, v99
	v_mul_f32_e32 v98, 0xbfb8aa3b, v96
	v_mul_f32_e32 v99, 0xbfb8aa3b, v97
	v_exp_f32_e32 v98, v98
	v_exp_f32_e32 v99, v99
	v_add_u32_e32 v114, s25, v175
	v_ashrrev_i32_e32 v115, 31, v114
	v_add_f32_e32 v98, 1.0, v98
	v_add_f32_e32 v99, 1.0, v99
	v_rcp_f32_e32 v98, v98
	v_rcp_f32_e32 v99, v99
	s_add_i32 s25, s25, 64
	s_cmpk_eq_i32 s25, 0x7c0
	v_pk_mul_f32 v[96:97], v[98:99], v[96:97]
	v_cvt_pk_bf16_f32 v99, v102, v103
	v_cvt_pk_bf16_f32 v102, v104, v105
	v_lshlrev_b64 v[104:105], 12, v[114:115]
	v_pk_mul_f32 v[106:107], v[96:97], v[106:107]
	v_cvt_pk_bf16_f32 v96, v118, v119
	v_cvt_pk_bf16_f32 v97, v100, v101
	v_cvt_pk_bf16_f32 v98, v112, v113
	v_lshl_add_u64 v[104:105], v[150:151], 0, v[104:105]
	v_cvt_pk_bf16_f32 v100, v108, v109
	v_cvt_pk_bf16_f32 v101, v110, v111
	v_cvt_pk_bf16_f32 v103, v106, v107
	global_store_dwordx4 v[104:105], v[96:99], off
	global_store_dwordx4 v[104:105], v[100:103], off offset:16
	s_cbranch_scc1 .LBB0_767
	s_waitcnt vmcnt(3)
	v_mov_b64_e32 v[102:103], v[26:27]
	s_waitcnt vmcnt(2)
	v_mov_b64_e32 v[98:99], v[18:19]
	v_mov_b64_e32 v[100:101], v[24:25]
	v_mov_b64_e32 v[96:97], v[16:17]
	s_and_saveexec_b64 s[36:37], s[4:5]
	s_cbranch_execz .LBB0_726

.LBB0_778:
	s_or_b64 exec, exec, s[4:5]
	s_waitcnt lgkmcnt(0)
	s_barrier
	v_mov_b32_e32 v204, 0x13c00
	ds_read_b32 v174, v204
	ds_read2_b64 v[244:247], v187 offset1:4
	v_add_u32_e32 v199, 0x4000, v187
	ds_read2_b64 v[248:251], v199 offset0:128 offset1:132
	ds_read2_b64 v[252:255], v187 offset0:8 offset1:12
	ds_read2_b64 v[200:203], v199 offset0:136 offset1:140
	v_cvt_pk_bf16_f32 v116, v52, v53
	v_cvt_pk_bf16_f32 v117, v54, v55
	v_cvt_pk_bf16_f32 v118, v48, v49
	v_cvt_pk_bf16_f32 v119, v50, v51
	v_cvt_pk_bf16_f32 v112, v44, v45
	v_cvt_pk_bf16_f32 v113, v46, v47
	v_cvt_pk_bf16_f32 v114, v20, v21
	v_cvt_pk_bf16_f32 v115, v22, v23
	v_cvt_pk_bf16_f32 v108, v40, v41
	v_cvt_pk_bf16_f32 v109, v42, v43
	v_cvt_pk_bf16_f32 v110, v36, v37
	v_cvt_pk_bf16_f32 v111, v38, v39
	v_cvt_pk_bf16_f32 v104, v32, v33
	v_cvt_pk_bf16_f32 v105, v34, v35
	v_cvt_pk_bf16_f32 v106, v28, v29
	v_cvt_pk_bf16_f32 v107, v30, v31
	s_waitcnt lgkmcnt(3)
	v_mfma_f32_16x16x32_bf16 v[120:123], v[244:247], v[116:119], 0
	ds_read2_b64 v[244:247], v187 offset0:16 offset1:20
	s_waitcnt lgkmcnt(3)
	v_mfma_f32_16x16x32_bf16 v[136:139], v[248:251], v[116:119], 0
	ds_read2_b64 v[248:251], v199 offset0:144 offset1:148
	s_waitcnt lgkmcnt(3)
	v_mfma_f32_16x16x32_bf16 v[120:123], v[252:255], v[112:115], v[120:123]
	ds_read2_b64 v[252:255], v187 offset0:24 offset1:28
	v_pk_mul_f32 v[52:53], v[52:53], v[174:175] op_sel_hi:[1,0]
	v_pk_mul_f32 v[54:55], v[54:55], v[174:175] op_sel_hi:[1,0]
	s_waitcnt lgkmcnt(3)
	v_mfma_f32_16x16x32_bf16 v[136:139], v[200:203], v[112:115], v[136:139]
	ds_read2_b64 v[200:203], v199 offset0:152 offset1:156
	v_pk_mul_f32 v[48:49], v[48:49], v[174:175] op_sel_hi:[1,0]
	s_waitcnt lgkmcnt(3)
	v_mfma_f32_16x16x32_bf16 v[120:123], v[244:247], v[108:111], v[120:123]
	v_add_u32_e32 v204, 0x1000, v187
	ds_read2_b64 v[244:247], v204 offset0:32 offset1:36
	v_pk_mul_f32 v[50:51], v[50:51], v[174:175] op_sel_hi:[1,0]
	v_pk_mul_f32 v[44:45], v[44:45], v[174:175] op_sel_hi:[1,0]
	s_waitcnt lgkmcnt(3)
	v_mfma_f32_16x16x32_bf16 v[136:139], v[248:251], v[108:111], v[136:139]
	v_add_u32_e32 v199, 0x5000, v187
	ds_read2_b64 v[248:251], v199 offset0:160 offset1:164
	v_pk_mul_f32 v[46:47], v[46:47], v[174:175] op_sel_hi:[1,0]
	s_waitcnt lgkmcnt(3)
	v_mfma_f32_16x16x32_bf16 v[120:123], v[252:255], v[104:107], v[120:123]
	ds_read2_b64 v[252:255], v204 offset0:40 offset1:44
	v_pk_mul_f32 v[20:21], v[20:21], v[174:175] op_sel_hi:[1,0]
	v_pk_mul_f32 v[22:23], v[22:23], v[174:175] op_sel_hi:[1,0]
	s_waitcnt lgkmcnt(3)
	v_mfma_f32_16x16x32_bf16 v[136:139], v[200:203], v[104:107], v[136:139]
	ds_read2_b64 v[200:203], v199 offset0:168 offset1:172
	v_pk_mul_f32 v[40:41], v[40:41], v[174:175] op_sel_hi:[1,0]
	s_waitcnt lgkmcnt(3)
	v_mfma_f32_16x16x32_bf16 v[124:127], v[244:247], v[116:119], 0
	ds_read2_b64 v[244:247], v204 offset0:48 offset1:52
	v_pk_mul_f32 v[42:43], v[42:43], v[174:175] op_sel_hi:[1,0]
	v_pk_mul_f32 v[36:37], v[36:37], v[174:175] op_sel_hi:[1,0]
	s_waitcnt lgkmcnt(3)
	v_mfma_f32_16x16x32_bf16 v[140:143], v[248:251], v[116:119], 0
	ds_read2_b64 v[248:251], v199 offset0:176 offset1:180
	v_pk_mul_f32 v[38:39], v[38:39], v[174:175] op_sel_hi:[1,0]
	s_waitcnt lgkmcnt(3)
	v_mfma_f32_16x16x32_bf16 v[124:127], v[252:255], v[112:115], v[124:127]
	ds_read2_b64 v[252:255], v204 offset0:56 offset1:60
	v_pk_mul_f32 v[32:33], v[32:33], v[174:175] op_sel_hi:[1,0]
	v_pk_mul_f32 v[34:35], v[34:35], v[174:175] op_sel_hi:[1,0]
	s_waitcnt lgkmcnt(3)
	v_mfma_f32_16x16x32_bf16 v[140:143], v[200:203], v[112:115], v[140:143]
	ds_read2_b64 v[200:203], v199 offset0:184 offset1:188
	v_pk_mul_f32 v[28:29], v[28:29], v[174:175] op_sel_hi:[1,0]
	s_waitcnt lgkmcnt(3)
	v_mfma_f32_16x16x32_bf16 v[124:127], v[244:247], v[108:111], v[124:127]
	v_add_u32_e32 v204, 0x2000, v187
	ds_read2_b64 v[244:247], v204 offset0:64 offset1:68
	v_pk_mul_f32 v[30:31], v[30:31], v[174:175] op_sel_hi:[1,0]
	s_waitcnt lgkmcnt(3)
	v_mfma_f32_16x16x32_bf16 v[140:143], v[248:251], v[108:111], v[140:143]
	v_add_u32_e32 v199, 0x6000, v187
	ds_read2_b64 v[248:251], v199 offset0:192 offset1:196
	s_waitcnt lgkmcnt(3)
	v_mfma_f32_16x16x32_bf16 v[124:127], v[252:255], v[104:107], v[124:127]
	ds_read2_b64 v[252:255], v204 offset0:72 offset1:76
	s_waitcnt lgkmcnt(3)
	v_mfma_f32_16x16x32_bf16 v[140:143], v[200:203], v[104:107], v[140:143]
	ds_read2_b64 v[200:203], v199 offset0:200 offset1:204
	s_waitcnt lgkmcnt(3)
	v_mfma_f32_16x16x32_bf16 v[128:131], v[244:247], v[116:119], 0
	ds_read2_b64 v[244:247], v204 offset0:80 offset1:84
	s_waitcnt lgkmcnt(3)
	v_mfma_f32_16x16x32_bf16 v[144:147], v[248:251], v[116:119], 0
	ds_read2_b64 v[248:251], v199 offset0:208 offset1:212
	s_waitcnt lgkmcnt(3)
	v_mfma_f32_16x16x32_bf16 v[128:131], v[252:255], v[112:115], v[128:131]
	ds_read2_b64 v[252:255], v204 offset0:88 offset1:92
	s_waitcnt lgkmcnt(3)
	v_mfma_f32_16x16x32_bf16 v[144:147], v[200:203], v[112:115], v[144:147]
	ds_read2_b64 v[200:203], v199 offset0:216 offset1:220
	s_waitcnt lgkmcnt(3)
	v_mfma_f32_16x16x32_bf16 v[128:131], v[244:247], v[108:111], v[128:131]
	v_add_u32_e32 v204, 0x3000, v187
	ds_read2_b64 v[244:247], v204 offset0:96 offset1:100
	s_waitcnt lgkmcnt(3)
	v_mfma_f32_16x16x32_bf16 v[144:147], v[248:251], v[108:111], v[144:147]
	v_add_u32_e32 v199, 0x7000, v187
	ds_read2_b64 v[248:251], v199 offset0:224 offset1:228
	s_waitcnt lgkmcnt(3)
	v_mfma_f32_16x16x32_bf16 v[128:131], v[252:255], v[104:107], v[128:131]
	ds_read2_b64 v[252:255], v204 offset0:104 offset1:108
	s_waitcnt lgkmcnt(3)
	v_mfma_f32_16x16x32_bf16 v[144:147], v[200:203], v[104:107], v[144:147]
	ds_read2_b64 v[200:203], v199 offset0:232 offset1:236
	s_waitcnt lgkmcnt(3)
	v_mfma_f32_16x16x32_bf16 v[132:135], v[244:247], v[116:119], 0
	ds_read2_b64 v[244:247], v204 offset0:112 offset1:116
	s_waitcnt lgkmcnt(3)
	v_mfma_f32_16x16x32_bf16 v[240:243], v[248:251], v[116:119], 0
	ds_read2_b64 v[248:251], v199 offset0:240 offset1:244
	s_waitcnt lgkmcnt(3)
	v_mfma_f32_16x16x32_bf16 v[132:135], v[252:255], v[112:115], v[132:135]
	ds_read2_b64 v[252:255], v204 offset0:120 offset1:124
	s_waitcnt lgkmcnt(3)
	v_mfma_f32_16x16x32_bf16 v[240:243], v[200:203], v[112:115], v[240:243]
	ds_read2_b64 v[200:203], v199 offset0:248 offset1:252
	s_waitcnt lgkmcnt(3)
	v_mfma_f32_16x16x32_bf16 v[132:135], v[244:247], v[108:111], v[132:135]
	v_add_u32_e32 v204, 0xf000, v186
	ds_read2_b64 v[244:247], v204 offset0:128 offset1:132
	s_waitcnt lgkmcnt(3)
	v_mfma_f32_16x16x32_bf16 v[240:243], v[248:251], v[108:111], v[240:243]
	ds_read2_b64 v[248:251], v204 offset0:136 offset1:140
	s_waitcnt lgkmcnt(3)
	v_mfma_f32_16x16x32_bf16 v[132:135], v[252:255], v[104:107], v[132:135]
	v_add_u32_e32 v199, 0x8800, v185
	ds_read2_b64 v[252:255], v199 offset1:4
	s_waitcnt lgkmcnt(3)
	v_mfma_f32_16x16x32_bf16 v[240:243], v[200:203], v[104:107], v[240:243]
	ds_read2_b64 v[200:203], v199 offset0:8 offset1:12
	s_waitcnt lgkmcnt(3)
	v_lshlrev_b32_e32 v104, 16, v244
	v_and_b32_e32 v105, 0xffff0000, v244
	v_lshlrev_b32_e32 v106, 16, v245
	v_and_b32_e32 v107, 0xffff0000, v245
	v_pk_add_f32 v[120:121], v[104:105], v[120:121] neg_lo:[0,1] neg_hi:[0,1]
	v_pk_add_f32 v[122:123], v[106:107], v[122:123] neg_lo:[0,1] neg_hi:[0,1]
	v_lshlrev_b32_e32 v108, 16, v246
	v_and_b32_e32 v109, 0xffff0000, v246
	v_lshlrev_b32_e32 v110, 16, v247
	v_and_b32_e32 v111, 0xffff0000, v247
	v_pk_add_f32 v[124:125], v[108:109], v[124:125] neg_lo:[0,1] neg_hi:[0,1]
	v_pk_add_f32 v[126:127], v[110:111], v[126:127] neg_lo:[0,1] neg_hi:[0,1]
	v_add_u32_e32 v204, 0x9000, v185
	ds_read2_b64 v[244:247], v204 offset0:32 offset1:36
	v_cvt_pk_bf16_f32 v116, v120, v121
	v_cvt_pk_bf16_f32 v117, v122, v123
	v_cvt_pk_bf16_f32 v118, v124, v125
	v_cvt_pk_bf16_f32 v119, v126, v127
	s_waitcnt lgkmcnt(3)
	v_lshlrev_b32_e32 v104, 16, v248
	v_and_b32_e32 v105, 0xffff0000, v248
	v_lshlrev_b32_e32 v106, 16, v249
	v_and_b32_e32 v107, 0xffff0000, v249
	v_pk_add_f32 v[128:129], v[104:105], v[128:129] neg_lo:[0,1] neg_hi:[0,1]
	v_pk_add_f32 v[130:131], v[106:107], v[130:131] neg_lo:[0,1] neg_hi:[0,1]
	v_lshlrev_b32_e32 v108, 16, v250
	v_and_b32_e32 v109, 0xffff0000, v250
	v_lshlrev_b32_e32 v110, 16, v251
	v_and_b32_e32 v111, 0xffff0000, v251
	v_pk_add_f32 v[132:133], v[108:109], v[132:133] neg_lo:[0,1] neg_hi:[0,1]
	v_pk_add_f32 v[134:135], v[110:111], v[134:135] neg_lo:[0,1] neg_hi:[0,1]
	ds_read2_b64 v[248:251], v204 offset0:40 offset1:44
	v_cvt_pk_bf16_f32 v112, v128, v129
	v_cvt_pk_bf16_f32 v113, v130, v131
	v_cvt_pk_bf16_f32 v114, v132, v133
	v_cvt_pk_bf16_f32 v115, v134, v135
	s_waitcnt lgkmcnt(3)
	s_nop 1
	v_mfma_f32_16x16x32_bf16 v[136:139], v[252:255], v[116:119], v[136:139]
	v_add_u32_e32 v199, 0x9800, v185
	ds_read2_b64 v[252:255], v199 offset0:64 offset1:68
	s_waitcnt lgkmcnt(3)
	v_mfma_f32_16x16x32_bf16 v[136:139], v[200:203], v[112:115], v[136:139]
	ds_read2_b64 v[200:203], v199 offset0:72 offset1:76
	s_waitcnt lgkmcnt(3)
	v_mfma_f32_16x16x32_bf16 v[140:143], v[244:247], v[116:119], v[140:143]
	v_add_u32_e32 v204, 0xa000, v185
	ds_read2_b64 v[244:247], v204 offset0:96 offset1:100
	s_waitcnt lgkmcnt(3)
	v_mfma_f32_16x16x32_bf16 v[140:143], v[248:251], v[112:115], v[140:143]
	ds_read2_b64 v[248:251], v204 offset0:104 offset1:108
	s_waitcnt lgkmcnt(3)
	v_mfma_f32_16x16x32_bf16 v[144:147], v[252:255], v[116:119], v[144:147]
	v_add_u32_e32 v199, 0xa800, v185
	ds_read2_b64 v[252:255], v199 offset0:128 offset1:132
	s_waitcnt lgkmcnt(3)
	v_mfma_f32_16x16x32_bf16 v[144:147], v[200:203], v[112:115], v[144:147]
	ds_read2_b64 v[200:203], v199 offset0:136 offset1:140
	s_waitcnt lgkmcnt(3)
	v_mfma_f32_16x16x32_bf16 v[240:243], v[244:247], v[116:119], v[240:243]
	v_add_u32_e32 v204, 0xb000, v185
	ds_read2_b64 v[244:247], v204 offset0:160 offset1:164
	s_waitcnt lgkmcnt(3)
	v_mfma_f32_16x16x32_bf16 v[240:243], v[248:251], v[112:115], v[240:243]
	ds_read2_b64 v[248:251], v204 offset0:168 offset1:172
	s_waitcnt lgkmcnt(3)
	v_mfma_f32_16x16x32_bf16 v[52:55], v[252:255], v[116:119], v[52:55]
	v_add_u32_e32 v199, 0xb800, v185
	ds_read2_b64 v[252:255], v199 offset0:192 offset1:196
	s_waitcnt lgkmcnt(3)
	v_mfma_f32_16x16x32_bf16 v[52:55], v[200:203], v[112:115], v[52:55]
	ds_read2_b64 v[200:203], v199 offset0:200 offset1:204
	s_waitcnt lgkmcnt(3)
	v_mfma_f32_16x16x32_bf16 v[48:51], v[244:247], v[116:119], v[48:51]
	v_add_u32_e32 v204, 0xc000, v185
	ds_read2_b64 v[244:247], v204 offset0:224 offset1:228
	s_waitcnt lgkmcnt(3)
	v_mfma_f32_16x16x32_bf16 v[48:51], v[248:251], v[112:115], v[48:51]
	ds_read2_b64 v[248:251], v204 offset0:232 offset1:236
	s_waitcnt lgkmcnt(3)
	v_mfma_f32_16x16x32_bf16 v[44:47], v[252:255], v[116:119], v[44:47]
	v_add_u32_e32 v199, 0xd000, v185
	ds_read2_b64 v[252:255], v199 offset1:4
	s_waitcnt lgkmcnt(3)
	v_mfma_f32_16x16x32_bf16 v[44:47], v[200:203], v[112:115], v[44:47]
	ds_read2_b64 v[200:203], v199 offset0:8 offset1:12
	s_waitcnt lgkmcnt(3)
	v_mfma_f32_16x16x32_bf16 v[20:23], v[244:247], v[116:119], v[20:23]
	v_add_u32_e32 v204, 0xd800, v185
	ds_read2_b64 v[244:247], v204 offset0:32 offset1:36
	s_waitcnt lgkmcnt(3)
	v_mfma_f32_16x16x32_bf16 v[20:23], v[248:251], v[112:115], v[20:23]
	ds_read2_b64 v[248:251], v204 offset0:40 offset1:44
	s_waitcnt lgkmcnt(3)
	v_mfma_f32_16x16x32_bf16 v[40:43], v[252:255], v[116:119], v[40:43]
	v_add_u32_e32 v199, 0xe000, v185
	ds_read2_b64 v[252:255], v199 offset0:64 offset1:68
	s_waitcnt lgkmcnt(3)
	v_mfma_f32_16x16x32_bf16 v[40:43], v[200:203], v[112:115], v[40:43]
	ds_read2_b64 v[200:203], v199 offset0:72 offset1:76
	s_waitcnt lgkmcnt(3)
	v_mfma_f32_16x16x32_bf16 v[36:39], v[244:247], v[116:119], v[36:39]
	v_add_u32_e32 v204, 0xe800, v185
	ds_read2_b64 v[244:247], v204 offset0:96 offset1:100
	s_waitcnt lgkmcnt(3)
	v_mfma_f32_16x16x32_bf16 v[36:39], v[248:251], v[112:115], v[36:39]
	ds_read2_b64 v[248:251], v204 offset0:104 offset1:108
	s_waitcnt lgkmcnt(3)
	v_mfma_f32_16x16x32_bf16 v[32:35], v[252:255], v[116:119], v[32:35]
	s_waitcnt lgkmcnt(2)
	v_mfma_f32_16x16x32_bf16 v[32:35], v[200:203], v[112:115], v[32:35]
	s_waitcnt lgkmcnt(1)
	v_mfma_f32_16x16x32_bf16 v[28:31], v[244:247], v[116:119], v[28:31]
	s_waitcnt lgkmcnt(0)
	v_mfma_f32_16x16x32_bf16 v[28:31], v[248:251], v[112:115], v[28:31]
	ds_write2_b32 v149, v136, v137 offset1:132
	v_add_u32_e32 v199, 0x400, v149
	ds_write2_b32 v199, v138, v139 offset0:8 offset1:140
	v_add_u32_e32 v199, 0x2000, v149
	ds_write2_b32 v199, v140, v141 offset0:64 offset1:196
	v_add_u32_e32 v199, 0x2400, v149
	ds_write2_b32 v199, v142, v143 offset0:72 offset1:204
	v_add_u32_e32 v199, 0x4200, v149
	ds_write2_b32 v199, v144, v145 offset1:132
	v_add_u32_e32 v199, 0x4600, v149
	ds_write2_b32 v199, v146, v147 offset0:8 offset1:140
	v_add_u32_e32 v199, 0x6200, v149
	ds_write2_b32 v199, v240, v241 offset0:64 offset1:196
	v_add_u32_e32 v199, 0x6600, v149
	ds_write2_b32 v199, v242, v243 offset0:72 offset1:204
	s_mov_b32 s4, 0x800000
	s_waitcnt lgkmcnt(0)
	s_barrier
	ds_read_b128 v[70:73], v184
	ds_read_b128 v[64:67], v184 offset:16
	ds_read_b128 v[60:63], v184 offset:32
	ds_read_b128 v[56:59], v184 offset:48
	s_waitcnt lgkmcnt(3)
	v_mov_b32_e32 v74, v71
	s_waitcnt lgkmcnt(2)
	v_mov_b32_e32 v75, v65
	v_mov_b32_e32 v68, v70
	v_mov_b32_e32 v69, v64
	v_pk_mul_f32 v[74:75], v[74:75], v[74:75]
	s_waitcnt lgkmcnt(1)
	v_mov_b32_e32 v76, v61
	v_pk_fma_f32 v[68:69], v[68:69], v[68:69], v[74:75]
	v_mov_b32_e32 v74, v72
	v_mov_b32_e32 v75, v66
	v_pk_fma_f32 v[68:69], v[74:75], v[74:75], v[68:69]
	v_mov_b32_e32 v74, v73
	v_mov_b32_e32 v75, v67
	s_waitcnt lgkmcnt(0)
	v_mov_b32_e32 v77, v57
	v_pk_fma_f32 v[68:69], v[74:75], v[74:75], v[68:69]
	v_mov_b32_e32 v74, v60
	v_mov_b32_e32 v75, v56
	v_pk_mul_f32 v[76:77], v[76:77], v[76:77]
	v_add_f32_e32 v68, v68, v69
	v_pk_fma_f32 v[74:75], v[74:75], v[74:75], v[76:77]
	v_mov_b32_e32 v76, v62
	v_mov_b32_e32 v77, v58
	v_pk_fma_f32 v[74:75], v[76:77], v[76:77], v[74:75]
	v_mov_b32_e32 v76, v63
	v_mov_b32_e32 v77, v59
	v_pk_fma_f32 v[74:75], v[76:77], v[76:77], v[74:75]
	s_nop 0
	v_add_f32_e32 v68, v68, v74
	v_add_f32_e32 v68, v68, v75
	ds_bpermute_b32 v69, v183, v68
	s_waitcnt vmcnt(3)
	v_lshlrev_b32_e32 v74, 16, v24
	v_and_b32_e32 v75, 0xffff0000, v24
	v_mul_f32_e32 v24, 0xbfb8aa3b, v74
	v_exp_f32_e32 v24, v24
	s_waitcnt lgkmcnt(0)
	v_add_f32_e32 v68, v68, v69
	ds_bpermute_b32 v69, v182, v68
	v_add_f32_e32 v24, 1.0, v24
	v_rcp_f32_e32 v76, v24
	v_mul_f32_e32 v24, 0xbfb8aa3b, v75
	s_waitcnt lgkmcnt(0)
	v_add_f32_e32 v68, v68, v69
	ds_bpermute_b32 v69, v177, v68
	v_exp_f32_e32 v24, v24
	s_waitcnt lgkmcnt(0)
	v_add_f32_e32 v68, v68, v69
	v_mov_b32_e32 v69, 0x358637bd
	v_fmac_f32_e32 v69, 0x3c000000, v68
	v_cmp_gt_f32_e32 vcc, s4, v69
	v_mul_f32_e32 v68, 0x4b800000, v69
	v_add_f32_e32 v24, 1.0, v24
	v_cndmask_b32_e32 v68, v69, v68, vcc
	v_rsq_f32_e32 v68, v68
	v_rcp_f32_e32 v77, v24
	v_lshlrev_b32_e32 v24, 16, v25
	v_and_b32_e32 v25, 0xffff0000, v25
	v_mul_f32_e32 v69, 0x45800000, v68
	v_cndmask_b32_e32 v68, v68, v69, vcc
	v_pk_mul_f32 v[70:71], v[70:71], v[68:69] op_sel_hi:[1,0]
	v_mul_f32_e32 v69, 0xbfb8aa3b, v24
	v_exp_f32_e32 v69, v69
	v_pk_mul_f32 v[12:13], v[12:13], v[70:71]
	v_pk_mul_f32 v[70:71], v[76:77], v[74:75]
	s_lshl_b64 s[4:5], s[2:3], 16
	v_add_f32_e32 v69, 1.0, v69
	v_pk_mul_f32 v[12:13], v[70:71], v[12:13]
	v_rcp_f32_e32 v70, v69
	v_pk_mul_f32 v[72:73], v[72:73], v[68:69] op_sel_hi:[1,0]
	v_mul_f32_e32 v69, 0xbfb8aa3b, v25
	v_exp_f32_e32 v69, v69
	v_pk_mul_f32 v[14:15], v[14:15], v[72:73]
	s_add_u32 s4, s28, s4
	s_addc_u32 s5, s29, s5
	v_add_f32_e32 v69, 1.0, v69
	v_rcp_f32_e32 v71, v69
	v_pk_mul_f32 v[64:65], v[64:65], v[68:69] op_sel_hi:[1,0]
	v_pk_mul_f32 v[60:61], v[60:61], v[68:69] op_sel_hi:[1,0]
	v_pk_mul_f32 v[8:9], v[8:9], v[64:65]
	v_pk_mul_f32 v[24:25], v[70:71], v[24:25]
	v_pk_mul_f32 v[64:65], v[66:67], v[68:69] op_sel_hi:[1,0]
	v_pk_mul_f32 v[14:15], v[24:25], v[14:15]
	v_lshlrev_b32_e32 v24, 16, v26
	v_and_b32_e32 v25, 0xffff0000, v26
	v_mul_f32_e32 v26, 0xbfb8aa3b, v24
	v_exp_f32_e32 v26, v26
	v_pk_mul_f32 v[10:11], v[10:11], v[64:65]
	v_pk_mul_f32 v[4:5], v[4:5], v[60:61]
	v_add_f32_e32 v26, 1.0, v26
	v_rcp_f32_e32 v70, v26
	v_mul_f32_e32 v26, 0xbfb8aa3b, v25
	v_exp_f32_e32 v26, v26
	s_nop 0
	v_add_f32_e32 v26, 1.0, v26
	v_rcp_f32_e32 v71, v26
	s_nop 0
	v_pk_mul_f32 v[24:25], v[70:71], v[24:25]
	s_nop 0
	v_pk_mul_f32 v[8:9], v[24:25], v[8:9]
	v_lshlrev_b32_e32 v24, 16, v27
	v_and_b32_e32 v25, 0xffff0000, v27
	v_mul_f32_e32 v26, 0xbfb8aa3b, v24
	v_mul_f32_e32 v27, 0xbfb8aa3b, v25
	v_exp_f32_e32 v26, v26
	v_exp_f32_e32 v27, v27
	v_add_f32_e32 v26, 1.0, v26
	v_add_f32_e32 v27, 1.0, v27
	v_rcp_f32_e32 v26, v26
	v_rcp_f32_e32 v27, v27
	s_nop 0
	v_pk_mul_f32 v[24:25], v[26:27], v[24:25]
	s_nop 0
	v_pk_mul_f32 v[10:11], v[24:25], v[10:11]
	s_waitcnt vmcnt(2)
	v_lshlrev_b32_e32 v24, 16, v16
	v_and_b32_e32 v25, 0xffff0000, v16
	v_mul_f32_e32 v16, 0xbfb8aa3b, v24
	v_exp_f32_e32 v16, v16
	s_nop 0
	v_add_f32_e32 v16, 1.0, v16
	v_rcp_f32_e32 v26, v16
	v_mul_f32_e32 v16, 0xbfb8aa3b, v25
	v_exp_f32_e32 v16, v16
	s_nop 0
	v_add_f32_e32 v16, 1.0, v16
	v_rcp_f32_e32 v27, v16
	v_lshlrev_b32_e32 v16, 16, v17
	v_and_b32_e32 v17, 0xffff0000, v17
	v_pk_mul_f32 v[24:25], v[26:27], v[24:25]
	s_nop 0
	v_pk_mul_f32 v[4:5], v[24:25], v[4:5]
	v_mul_f32_e32 v24, 0xbfb8aa3b, v16
	v_mul_f32_e32 v25, 0xbfb8aa3b, v17
	v_exp_f32_e32 v24, v24
	v_exp_f32_e32 v25, v25
	v_pk_mul_f32 v[26:27], v[62:63], v[68:69] op_sel_hi:[1,0]
	v_cvt_pk_bf16_f32 v4, v4, v5
	v_add_f32_e32 v24, 1.0, v24
	v_add_f32_e32 v25, 1.0, v25
	v_rcp_f32_e32 v24, v24
	v_rcp_f32_e32 v25, v25
	v_pk_mul_f32 v[6:7], v[6:7], v[26:27]
	v_pk_mul_f32 v[26:27], v[56:57], v[68:69] op_sel_hi:[1,0]
	v_pk_mul_f32 v[16:17], v[24:25], v[16:17]
	s_nop 0
	v_pk_mul_f32 v[6:7], v[16:17], v[6:7]
	v_lshlrev_b32_e32 v16, 16, v18
	v_and_b32_e32 v17, 0xffff0000, v18
	v_mul_f32_e32 v18, 0xbfb8aa3b, v16
	v_exp_f32_e32 v18, v18
	v_pk_mul_f32 v[0:1], v[0:1], v[26:27]
	v_cvt_pk_bf16_f32 v5, v6, v7
	v_add_f32_e32 v18, 1.0, v18
	v_rcp_f32_e32 v24, v18
	v_mul_f32_e32 v18, 0xbfb8aa3b, v17
	v_exp_f32_e32 v18, v18
	s_nop 0
	v_add_f32_e32 v18, 1.0, v18
	v_rcp_f32_e32 v25, v18
	s_nop 0
	v_pk_mul_f32 v[16:17], v[24:25], v[16:17]
	s_nop 0
	v_pk_mul_f32 v[16:17], v[16:17], v[0:1]
	v_lshlrev_b32_e32 v0, 16, v19
	v_and_b32_e32 v1, 0xffff0000, v19
	v_mul_f32_e32 v18, 0xbfb8aa3b, v0
	v_mul_f32_e32 v19, 0xbfb8aa3b, v1
	v_exp_f32_e32 v18, v18
	v_exp_f32_e32 v19, v19
	v_pk_mul_f32 v[24:25], v[58:59], v[68:69] op_sel_hi:[1,0]
	v_cvt_pk_bf16_f32 v6, v16, v17
	v_add_f32_e32 v18, 1.0, v18
	v_add_f32_e32 v19, 1.0, v19
	v_rcp_f32_e32 v18, v18
	v_rcp_f32_e32 v19, v19
	v_pk_mul_f32 v[2:3], v[2:3], v[24:25]
	v_add_u32_e32 v24, 0x7c0, v175
	v_ashrrev_i32_e32 v25, 31, v24
	v_pk_mul_f32 v[0:1], v[18:19], v[0:1]
	s_nop 0
	v_pk_mul_f32 v[18:19], v[0:1], v[2:3]
	v_cvt_pk_bf16_f32 v2, v8, v9
	v_lshlrev_b64 v[8:9], 12, v[24:25]
	v_cvt_pk_bf16_f32 v0, v12, v13
	v_cvt_pk_bf16_f32 v1, v14, v15
	v_cvt_pk_bf16_f32 v3, v10, v11
	v_lshl_add_u64 v[8:9], v[150:151], 0, v[8:9]
	v_cvt_pk_bf16_f32 v7, v18, v19
	global_store_dwordx4 v[8:9], v[0:3], off
	global_store_dwordx4 v[8:9], v[4:7], off offset:16
	s_nop 0
	v_lshlrev_b32_e32 v0, 7, v148
	v_and_b32_e32 v0, 0x1800, v0
	v_mov_b32_e32 v1, 0
	v_lshl_add_u64 v[2:3], s[4:5], 0, v[0:1]
	v_ashrrev_i32_e32 v0, 2, v148
	v_and_b32_e32 v4, -16, v0
	v_ashrrev_i32_e32 v5, 31, v4
	v_and_b32_e32 v0, 15, v148
	v_lshl_add_u64 v[2:3], v[4:5], 2, v[2:3]
	v_lshlrev_b32_e32 v0, 2, v0
	v_lshl_add_u64 v[0:1], v[2:3], 0, v[0:1]
	s_mov_b64 s[4:5], 0x4824000
	v_lshl_add_u64 v[2:3], v[0:1], 0, s[4:5]
	s_mov_b32 s4, 0x4824000
	v_add_co_u32_e32 v4, vcc, s4, v0
	s_mov_b32 s4, 0x4826000
	s_nop 0
	v_addc_co_u32_e32 v5, vcc, 0, v1, vcc
	global_store_dword v[4:5], v52, off
	global_store_dword v[2:3], v53, off offset:512
	global_store_dword v[2:3], v54, off offset:1024
	global_store_dword v[2:3], v55, off offset:1536
	v_add_co_u32_e32 v2, vcc, s4, v0
	s_mov_b32 s4, 0x4828000
	s_nop 0
	v_addc_co_u32_e32 v3, vcc, 0, v1, vcc
	global_store_dword v[2:3], v48, off
	global_store_dword v[2:3], v49, off offset:512
	global_store_dword v[2:3], v50, off offset:1024
	global_store_dword v[2:3], v51, off offset:1536
	v_add_co_u32_e32 v2, vcc, s4, v0
	s_mov_b32 s4, 0x482a000
	s_nop 0
	v_addc_co_u32_e32 v3, vcc, 0, v1, vcc
	global_store_dword v[2:3], v44, off
	global_store_dword v[2:3], v45, off offset:512
	global_store_dword v[2:3], v46, off offset:1024
	global_store_dword v[2:3], v47, off offset:1536
	v_add_co_u32_e32 v2, vcc, s4, v0
	s_mov_b32 s4, 0x482c000
	s_nop 0
	v_addc_co_u32_e32 v3, vcc, 0, v1, vcc
	global_store_dword v[2:3], v20, off
	global_store_dword v[2:3], v21, off offset:512
	global_store_dword v[2:3], v22, off offset:1024
	global_store_dword v[2:3], v23, off offset:1536
	v_add_co_u32_e32 v2, vcc, s4, v0
	s_mov_b32 s4, 0x482e000
	s_nop 0
	v_addc_co_u32_e32 v3, vcc, 0, v1, vcc
	global_store_dword v[2:3], v40, off
	global_store_dword v[2:3], v41, off offset:512
	global_store_dword v[2:3], v42, off offset:1024
	global_store_dword v[2:3], v43, off offset:1536
	v_add_co_u32_e32 v2, vcc, s4, v0
	s_mov_b32 s4, 0x4830000
	s_nop 0
	v_addc_co_u32_e32 v3, vcc, 0, v1, vcc
	global_store_dword v[2:3], v36, off
	global_store_dword v[2:3], v37, off offset:512
	global_store_dword v[2:3], v38, off offset:1024
	global_store_dword v[2:3], v39, off offset:1536
	v_add_co_u32_e32 v2, vcc, s4, v0
	s_nop 1
	v_addc_co_u32_e32 v3, vcc, 0, v1, vcc
	v_add_co_u32_e32 v0, vcc, 0x4832000, v0
	global_store_dword v[2:3], v32, off
	global_store_dword v[2:3], v33, off offset:512
	global_store_dword v[2:3], v34, off offset:1024
	global_store_dword v[2:3], v35, off offset:1536
	v_addc_co_u32_e32 v1, vcc, 0, v1, vcc
	global_store_dword v[0:1], v28, off
	global_store_dword v[0:1], v29, off offset:512
	global_store_dword v[0:1], v30, off offset:1024
	global_store_dword v[0:1], v31, off offset:1536

	.amdhsa_kernel _Z9hymba_fwd6Params
		.amdhsa_group_segment_fixed_size 0
		.amdhsa_private_segment_fixed_size 0
		.amdhsa_kernarg_size 464
		.amdhsa_user_sgpr_count 2
		.amdhsa_user_sgpr_dispatch_ptr 0
		.amdhsa_user_sgpr_queue_ptr 0
		.amdhsa_user_sgpr_kernarg_segment_ptr 1
		.amdhsa_user_sgpr_dispatch_id 0
		.amdhsa_user_sgpr_kernarg_preload_length 0
		.amdhsa_user_sgpr_kernarg_preload_offset 0
		.amdhsa_user_sgpr_private_segment_size 0
		.amdhsa_uses_dynamic_stack 0
		.amdhsa_enable_private_segment 0
		.amdhsa_system_sgpr_workgroup_id_x 1
		.amdhsa_system_sgpr_workgroup_id_y 0
		.amdhsa_system_sgpr_workgroup_id_z 0
		.amdhsa_system_sgpr_workgroup_info 0
		.amdhsa_system_vgpr_workitem_id 2
		.amdhsa_next_free_vgpr 256
		.amdhsa_next_free_sgpr 102
		.amdhsa_accum_offset 256
		.amdhsa_reserve_vcc 1
		.amdhsa_float_round_mode_32 0
		.amdhsa_float_round_mode_16_64 0
		.amdhsa_float_denorm_mode_32 3
		.amdhsa_float_denorm_mode_16_64 3
		.amdhsa_dx10_clamp 1
		.amdhsa_ieee_mode 1
		.amdhsa_fp16_overflow 0
		.amdhsa_tg_split 0
		.amdhsa_exception_fp_ieee_invalid_op 0
		.amdhsa_exception_fp_denorm_src 0
		.amdhsa_exception_fp_ieee_div_zero 0
		.amdhsa_exception_fp_ieee_overflow 0
		.amdhsa_exception_fp_ieee_underflow 0
		.amdhsa_exception_fp_ieee_inexact 0
		.amdhsa_exception_int_div_zero 0
	.end_amdhsa_kernel

amdhsa.kernels:
  - .agpr_count:     0
    .args:
      - .offset:         0
        .size:           208
        .value_kind:     by_value
      - .offset:         208
        .size:           4
        .value_kind:     hidden_block_count_x
      - .offset:         212
        .size:           4
        .value_kind:     hidden_block_count_y
      - .offset:         216
        .size:           4
        .value_kind:     hidden_block_count_z
      - .offset:         220
        .size:           2
        .value_kind:     hidden_group_size_x
      - .offset:         222
        .size:           2
        .value_kind:     hidden_group_size_y
      - .offset:         224
        .size:           2
        .value_kind:     hidden_group_size_z
      - .offset:         226
        .size:           2
        .value_kind:     hidden_remainder_x
      - .offset:         228
        .size:           2
        .value_kind:     hidden_remainder_y
      - .offset:         230
        .size:           2
        .value_kind:     hidden_remainder_z
      - .offset:         248
        .size:           8
        .value_kind:     hidden_global_offset_x
      - .offset:         256
        .size:           8
        .value_kind:     hidden_global_offset_y
      - .offset:         264
        .size:           8
        .value_kind:     hidden_global_offset_z
      - .offset:         272
        .size:           2
        .value_kind:     hidden_grid_dims
      - .offset:         296
        .size:           8
        .value_kind:     hidden_multigrid_sync_arg
      - .offset:         328
        .size:           4
        .value_kind:     hidden_dynamic_lds_size
    .group_segment_fixed_size: 0
    .kernarg_segment_align: 8
    .kernarg_segment_size: 464
    .language:       OpenCL C
    .language_version:
      - 2
      - 0
    .max_flat_workgroup_size: 512
    .name:           _Z9hymba_fwd6Params
    .private_segment_fixed_size: 0
    .sgpr_count:     108
    .sgpr_spill_count: 161
    .symbol:         _Z9hymba_fwd6Params.kd
    .uniform_work_group_size: 1
    .uses_dynamic_stack: false
    .vgpr_count:     256
    .vgpr_spill_count: 0
    .wavefront_size: 64
